# v16: v13 + MFMA-block s_setprio 1 issued before the barrier (compute segment opens with bare MFMAs)
# speedup vs baseline: 1.0103x; 1.0082x over previous
.LBB0_271:
	s_add_u32 s26, s14, 0xfffc0080
	s_addc_u32 s27, s15, -1
	s_add_i32 s54, 0, 0x10000
	s_cmp_eq_u32 s53, 12
	s_cselect_b32 s29, s21, s27
	s_cselect_b32 s28, s49, s26
	v_add_u32_e32 v154, s54, v141
	s_cselect_b32 s27, s19, s52
	s_cselect_b32 s26, s50, s51
	s_add_i32 s56, 0, 0x14000
	ds_read_b128 v[146:149], v154
	ds_read_b128 v[150:153], v154 offset:1024
	ds_read_b128 v[162:165], v154 offset:2048
	ds_read_b128 v[166:169], v154 offset:3072
	v_add_u32_e32 v154, s56, v141
	ds_read_b128 v[170:173], v154
	ds_read_b128 v[186:189], v154 offset:1024
	ds_read_b128 v[190:193], v154 offset:2048
	ds_read_b128 v[194:197], v154 offset:3072
	v_lshl_add_u64 v[154:155], s[14:15], 0, v[136:137]
	s_add_i32 m0, s37, 0xc000
	ds_read_b128 v[198:201], v145
	ds_read_b128 v[202:205], v145 offset:1024
	ds_read_b128 v[206:209], v145 offset:2048
	ds_read_b128 v[210:213], v145 offset:3072
	ds_read_b128 v[214:217], v145 offset:4096
	ds_read_b128 v[218:221], v145 offset:5120
	ds_read_b128 v[222:225], v145 offset:6144
	ds_read_b128 v[226:229], v145 offset:7168
	global_load_lds_dwordx4 v[154:155], off
	v_lshl_add_u64 v[154:155], s[14:15], 0, v[138:139]
	s_add_i32 m0, s37, 0xe000
	s_nop 0
	global_load_lds_dwordx4 v[154:155], off
	s_setprio 1
	s_waitcnt vmcnt(8) lgkmcnt(0)
	s_barrier
	v_mfma_f32_16x16x32_bf16 v[126:129], v[146:149], v[198:201], v[126:129]
	v_mfma_f32_16x16x32_bf16 v[122:125], v[162:165], v[198:201], v[122:125]
	v_mfma_f32_16x16x32_bf16 v[110:113], v[146:149], v[206:209], v[110:113]
	v_mfma_f32_16x16x32_bf16 v[106:109], v[162:165], v[206:209], v[106:109]
	v_mfma_f32_16x16x32_bf16 v[92:95], v[146:149], v[214:217], v[92:95]
	v_mfma_f32_16x16x32_bf16 v[88:91], v[162:165], v[214:217], v[88:91]
	v_mfma_f32_16x16x32_bf16 v[76:79], v[146:149], v[222:225], v[76:79]
	v_mfma_f32_16x16x32_bf16 v[72:75], v[162:165], v[222:225], v[72:75]
	v_mfma_f32_16x16x32_bf16 v[126:129], v[150:153], v[202:205], v[126:129]
	v_mfma_f32_16x16x32_bf16 v[122:125], v[166:169], v[202:205], v[122:125]
	v_mfma_f32_16x16x32_bf16 v[110:113], v[150:153], v[210:213], v[110:113]
	v_mfma_f32_16x16x32_bf16 v[106:109], v[166:169], v[210:213], v[106:109]
	v_mfma_f32_16x16x32_bf16 v[92:95], v[150:153], v[218:221], v[92:95]
	v_mfma_f32_16x16x32_bf16 v[88:91], v[166:169], v[218:221], v[88:91]
	v_mfma_f32_16x16x32_bf16 v[76:79], v[150:153], v[226:229], v[76:79]
	v_mfma_f32_16x16x32_bf16 v[72:75], v[166:169], v[226:229], v[72:75]
	s_setprio 0
	s_setprio 1
	v_mfma_f32_16x16x32_bf16 v[118:121], v[170:173], v[198:201], v[118:121]
	v_mfma_f32_16x16x32_bf16 v[114:117], v[190:193], v[198:201], v[114:117]
	v_mfma_f32_16x16x32_bf16 v[102:105], v[170:173], v[206:209], v[102:105]
	v_mfma_f32_16x16x32_bf16 v[98:101], v[190:193], v[206:209], v[98:101]
	v_mfma_f32_16x16x32_bf16 v[84:87], v[170:173], v[214:217], v[84:87]
	v_mfma_f32_16x16x32_bf16 v[80:83], v[190:193], v[214:217], v[80:83]
	v_mfma_f32_16x16x32_bf16 v[68:71], v[170:173], v[222:225], v[68:71]
	v_mfma_f32_16x16x32_bf16 v[64:67], v[190:193], v[222:225], v[64:67]
	v_mfma_f32_16x16x32_bf16 v[118:121], v[186:189], v[202:205], v[118:121]
	v_mfma_f32_16x16x32_bf16 v[114:117], v[194:197], v[202:205], v[114:117]
	v_mfma_f32_16x16x32_bf16 v[102:105], v[186:189], v[210:213], v[102:105]
	v_mfma_f32_16x16x32_bf16 v[98:101], v[194:197], v[210:213], v[98:101]
	v_mfma_f32_16x16x32_bf16 v[84:87], v[186:189], v[218:221], v[84:87]
	v_mfma_f32_16x16x32_bf16 v[80:83], v[194:197], v[218:221], v[80:83]
	v_mfma_f32_16x16x32_bf16 v[68:71], v[186:189], v[226:229], v[68:71]
	v_mfma_f32_16x16x32_bf16 v[64:67], v[194:197], v[226:229], v[64:67]
	s_setprio 0
	s_barrier
	s_setprio 2
	s_add_i32 s54, s54, s36
	v_lshl_add_u64 v[154:155], s[26:27], 0, v[96:97]
	s_mov_b32 m0, s54
	ds_read_b128 v[198:201], v145 offset:16384
	ds_read_b128 v[202:205], v145 offset:17408
	ds_read_b128 v[206:209], v145 offset:18432
	ds_read_b128 v[210:213], v145 offset:19456
	ds_read_b128 v[214:217], v145 offset:20480
	ds_read_b128 v[218:221], v145 offset:21504
	ds_read_b128 v[222:225], v145 offset:22528
	ds_read_b128 v[226:229], v145 offset:23552
	global_load_lds_dwordx4 v[154:155], off
	s_add_i32 m0, s54, 0x2000
	s_add_u32 s54, s26, 0x40000
	v_lshl_add_u64 v[156:157], s[26:27], 0, v[130:131]
	s_addc_u32 s55, s27, 0
	s_add_i32 s56, s56, s36
	global_load_lds_dwordx4 v[156:157], off
	v_lshl_add_u64 v[158:159], s[54:55], 0, v[96:97]
	s_mov_b32 m0, s56
	v_lshl_add_u64 v[182:183], s[28:29], 0, v[132:133]
	global_load_lds_dwordx4 v[158:159], off
	v_lshl_add_u64 v[158:159], s[54:55], 0, v[130:131]
	s_add_i32 m0, s56, 0x2000
	s_nop 0
	global_load_lds_dwordx4 v[158:159], off
	v_lshl_add_u64 v[158:159], s[28:29], 0, v[134:135]
	s_mov_b32 m0, s37
	s_nop 0
	global_load_lds_dwordx4 v[158:159], off
	s_mov_b32 m0, s38
	s_nop 0
	global_load_lds_dwordx4 v[182:183], off
	s_setprio 1
	s_waitcnt vmcnt(8) lgkmcnt(0)
	s_barrier
	v_mfma_f32_16x16x32_bf16 v[60:63], v[146:149], v[198:201], v[60:63]
	v_mfma_f32_16x16x32_bf16 v[56:59], v[162:165], v[198:201], v[56:59]
	v_mfma_f32_16x16x32_bf16 v[44:47], v[146:149], v[206:209], v[44:47]
	v_mfma_f32_16x16x32_bf16 v[40:43], v[162:165], v[206:209], v[40:43]
	v_mfma_f32_16x16x32_bf16 v[28:31], v[146:149], v[214:217], v[28:31]
	v_mfma_f32_16x16x32_bf16 v[24:27], v[162:165], v[214:217], v[24:27]
	v_mfma_f32_16x16x32_bf16 v[12:15], v[146:149], v[222:225], v[12:15]
	v_mfma_f32_16x16x32_bf16 v[4:7], v[162:165], v[222:225], v[4:7]
	v_mfma_f32_16x16x32_bf16 v[60:63], v[150:153], v[202:205], v[60:63]
	v_mfma_f32_16x16x32_bf16 v[56:59], v[166:169], v[202:205], v[56:59]
	v_mfma_f32_16x16x32_bf16 v[44:47], v[150:153], v[210:213], v[44:47]
	v_mfma_f32_16x16x32_bf16 v[40:43], v[166:169], v[210:213], v[40:43]
	v_mfma_f32_16x16x32_bf16 v[28:31], v[150:153], v[218:221], v[28:31]
	v_mfma_f32_16x16x32_bf16 v[24:27], v[166:169], v[218:221], v[24:27]
	v_mfma_f32_16x16x32_bf16 v[12:15], v[150:153], v[226:229], v[12:15]
	v_mfma_f32_16x16x32_bf16 v[4:7], v[166:169], v[226:229], v[4:7]
	s_setprio 0
	s_setprio 1
	v_mfma_f32_16x16x32_bf16 v[52:55], v[170:173], v[198:201], v[52:55]
	v_mfma_f32_16x16x32_bf16 v[48:51], v[190:193], v[198:201], v[48:51]
	v_mfma_f32_16x16x32_bf16 v[36:39], v[170:173], v[206:209], v[36:39]
	v_mfma_f32_16x16x32_bf16 v[32:35], v[190:193], v[206:209], v[32:35]
	v_mfma_f32_16x16x32_bf16 v[20:23], v[170:173], v[214:217], v[20:23]
	v_mfma_f32_16x16x32_bf16 v[16:19], v[190:193], v[214:217], v[16:19]
	v_mfma_f32_16x16x32_bf16 v[8:11], v[170:173], v[222:225], v[8:11]
	v_mfma_f32_16x16x32_bf16 v[0:3], v[190:193], v[222:225], v[0:3]
	v_mfma_f32_16x16x32_bf16 v[52:55], v[186:189], v[202:205], v[52:55]
	v_mfma_f32_16x16x32_bf16 v[48:51], v[194:197], v[202:205], v[48:51]
	v_mfma_f32_16x16x32_bf16 v[36:39], v[186:189], v[210:213], v[36:39]
	v_mfma_f32_16x16x32_bf16 v[32:35], v[194:197], v[210:213], v[32:35]
	v_mfma_f32_16x16x32_bf16 v[20:23], v[186:189], v[218:221], v[20:23]
	v_mfma_f32_16x16x32_bf16 v[16:19], v[194:197], v[218:221], v[16:19]
	v_mfma_f32_16x16x32_bf16 v[8:11], v[186:189], v[226:229], v[8:11]
	v_mfma_f32_16x16x32_bf16 v[0:3], v[194:197], v[226:229], v[0:3]
	s_setprio 0
	s_barrier
	s_setprio 2
	s_add_i32 s54, 0, 0x18000
	s_add_i32 s55, 0, 0x1c000
	v_add_u32_e32 v166, s54, v141
	v_add_u32_e32 v184, s55, v141
	ds_read_b128 v[146:149], v166
	ds_read_b128 v[150:153], v166 offset:1024
	ds_read_b128 v[162:165], v166 offset:2048
	ds_read_b128 v[166:169], v166 offset:3072
	ds_read_b128 v[170:173], v184
	ds_read_b128 v[186:189], v184 offset:1024
	ds_read_b128 v[190:193], v184 offset:2048
	ds_read_b128 v[194:197], v184 offset:3072
	s_add_u32 s28, s28, 0x40000
	s_addc_u32 s29, s29, 0
	s_mov_b32 m0, s39
	v_lshl_add_u64 v[184:185], s[28:29], 0, v[134:135]
	ds_read_b128 v[198:201], v145 offset:32768
	ds_read_b128 v[202:205], v145 offset:33792
	ds_read_b128 v[206:209], v145 offset:34816
	ds_read_b128 v[210:213], v145 offset:35840
	ds_read_b128 v[214:217], v145 offset:36864
	ds_read_b128 v[218:221], v145 offset:37888
	ds_read_b128 v[222:225], v145 offset:38912
	ds_read_b128 v[226:229], v145 offset:39936
	global_load_lds_dwordx4 v[184:185], off
	v_lshl_add_u64 v[184:185], s[28:29], 0, v[132:133]
	s_mov_b32 m0, s40
	s_nop 0
	global_load_lds_dwordx4 v[184:185], off
	s_setprio 1
	s_waitcnt vmcnt(8) lgkmcnt(0)
	s_barrier
	v_mfma_f32_16x16x32_bf16 v[126:129], v[146:149], v[198:201], v[126:129]
	v_mfma_f32_16x16x32_bf16 v[122:125], v[162:165], v[198:201], v[122:125]
	v_mfma_f32_16x16x32_bf16 v[110:113], v[146:149], v[206:209], v[110:113]
	v_mfma_f32_16x16x32_bf16 v[106:109], v[162:165], v[206:209], v[106:109]
	v_mfma_f32_16x16x32_bf16 v[92:95], v[146:149], v[214:217], v[92:95]
	v_mfma_f32_16x16x32_bf16 v[88:91], v[162:165], v[214:217], v[88:91]
	v_mfma_f32_16x16x32_bf16 v[76:79], v[146:149], v[222:225], v[76:79]
	v_mfma_f32_16x16x32_bf16 v[72:75], v[162:165], v[222:225], v[72:75]
	v_mfma_f32_16x16x32_bf16 v[126:129], v[150:153], v[202:205], v[126:129]
	v_mfma_f32_16x16x32_bf16 v[122:125], v[166:169], v[202:205], v[122:125]
	v_mfma_f32_16x16x32_bf16 v[110:113], v[150:153], v[210:213], v[110:113]
	v_mfma_f32_16x16x32_bf16 v[106:109], v[166:169], v[210:213], v[106:109]
	v_mfma_f32_16x16x32_bf16 v[92:95], v[150:153], v[218:221], v[92:95]
	v_mfma_f32_16x16x32_bf16 v[88:91], v[166:169], v[218:221], v[88:91]
	v_mfma_f32_16x16x32_bf16 v[76:79], v[150:153], v[226:229], v[76:79]
	v_mfma_f32_16x16x32_bf16 v[72:75], v[166:169], v[226:229], v[72:75]
	s_setprio 0
	s_setprio 1
	v_mfma_f32_16x16x32_bf16 v[118:121], v[170:173], v[198:201], v[118:121]
	v_mfma_f32_16x16x32_bf16 v[114:117], v[190:193], v[198:201], v[114:117]
	v_mfma_f32_16x16x32_bf16 v[102:105], v[170:173], v[206:209], v[102:105]
	v_mfma_f32_16x16x32_bf16 v[98:101], v[190:193], v[206:209], v[98:101]
	v_mfma_f32_16x16x32_bf16 v[84:87], v[170:173], v[214:217], v[84:87]
	v_mfma_f32_16x16x32_bf16 v[80:83], v[190:193], v[214:217], v[80:83]
	v_mfma_f32_16x16x32_bf16 v[68:71], v[170:173], v[222:225], v[68:71]
	v_mfma_f32_16x16x32_bf16 v[64:67], v[190:193], v[222:225], v[64:67]
	v_mfma_f32_16x16x32_bf16 v[118:121], v[186:189], v[202:205], v[118:121]
	v_mfma_f32_16x16x32_bf16 v[114:117], v[194:197], v[202:205], v[114:117]
	v_mfma_f32_16x16x32_bf16 v[102:105], v[186:189], v[210:213], v[102:105]
	v_mfma_f32_16x16x32_bf16 v[98:101], v[194:197], v[210:213], v[98:101]
	v_mfma_f32_16x16x32_bf16 v[84:87], v[186:189], v[218:221], v[84:87]
	v_mfma_f32_16x16x32_bf16 v[80:83], v[194:197], v[218:221], v[80:83]
	v_mfma_f32_16x16x32_bf16 v[68:71], v[186:189], v[226:229], v[68:71]
	v_mfma_f32_16x16x32_bf16 v[64:67], v[194:197], v[226:229], v[64:67]
	s_setprio 0
	s_barrier
	s_setprio 2
	s_add_i32 s28, s54, s36
	v_lshl_add_u64 v[154:155], v[154:155], 0, s[16:17]
	s_mov_b32 m0, s28
	ds_read_b128 v[198:201], v145 offset:49152
	ds_read_b128 v[202:205], v145 offset:50176
	ds_read_b128 v[206:209], v145 offset:51200
	ds_read_b128 v[210:213], v145 offset:52224
	ds_read_b128 v[214:217], v145 offset:53248
	ds_read_b128 v[218:221], v145 offset:54272
	ds_read_b128 v[222:225], v145 offset:55296
	ds_read_b128 v[226:229], v145 offset:56320
	global_load_lds_dwordx4 v[154:155], off
	s_add_i32 m0, s28, 0x2000
	s_add_u32 s26, s26, 0x40080
	v_lshl_add_u64 v[154:155], v[156:157], 0, s[16:17]
	s_addc_u32 s27, s27, 0
	s_add_i32 s28, s55, s36
	global_load_lds_dwordx4 v[154:155], off
	v_lshl_add_u64 v[154:155], s[26:27], 0, v[96:97]
	s_mov_b32 m0, s28
	s_nop 0
	global_load_lds_dwordx4 v[154:155], off
	v_lshl_add_u64 v[154:155], s[26:27], 0, v[130:131]
	s_add_i32 m0, s28, 0x2000
	s_nop 0
	global_load_lds_dwordx4 v[154:155], off
	v_lshl_add_u64 v[154:155], v[158:159], 0, s[16:17]
	s_mov_b32 m0, s41
	s_nop 0
	global_load_lds_dwordx4 v[154:155], off
	v_lshl_add_u64 v[154:155], v[182:183], 0, s[16:17]
	s_mov_b32 m0, s42
	s_nop 0
	global_load_lds_dwordx4 v[154:155], off
	s_setprio 1
	s_waitcnt vmcnt(8) lgkmcnt(0)
	s_barrier
	v_mfma_f32_16x16x32_bf16 v[60:63], v[146:149], v[198:201], v[60:63]
	v_mfma_f32_16x16x32_bf16 v[56:59], v[162:165], v[198:201], v[56:59]
	v_mfma_f32_16x16x32_bf16 v[44:47], v[146:149], v[206:209], v[44:47]
	v_mfma_f32_16x16x32_bf16 v[40:43], v[162:165], v[206:209], v[40:43]
	v_mfma_f32_16x16x32_bf16 v[28:31], v[146:149], v[214:217], v[28:31]
	v_mfma_f32_16x16x32_bf16 v[24:27], v[162:165], v[214:217], v[24:27]
	v_mfma_f32_16x16x32_bf16 v[12:15], v[146:149], v[222:225], v[12:15]
	v_mfma_f32_16x16x32_bf16 v[4:7], v[162:165], v[222:225], v[4:7]
	v_mfma_f32_16x16x32_bf16 v[60:63], v[150:153], v[202:205], v[60:63]
	v_mfma_f32_16x16x32_bf16 v[56:59], v[166:169], v[202:205], v[56:59]
	v_mfma_f32_16x16x32_bf16 v[44:47], v[150:153], v[210:213], v[44:47]
	v_mfma_f32_16x16x32_bf16 v[40:43], v[166:169], v[210:213], v[40:43]
	v_mfma_f32_16x16x32_bf16 v[28:31], v[150:153], v[218:221], v[28:31]
	v_mfma_f32_16x16x32_bf16 v[24:27], v[166:169], v[218:221], v[24:27]
	v_mfma_f32_16x16x32_bf16 v[12:15], v[150:153], v[226:229], v[12:15]
	v_mfma_f32_16x16x32_bf16 v[4:7], v[166:169], v[226:229], v[4:7]
	s_setprio 0
	s_setprio 1
	v_mfma_f32_16x16x32_bf16 v[52:55], v[170:173], v[198:201], v[52:55]
	v_mfma_f32_16x16x32_bf16 v[48:51], v[190:193], v[198:201], v[48:51]
	v_mfma_f32_16x16x32_bf16 v[36:39], v[170:173], v[206:209], v[36:39]
	v_mfma_f32_16x16x32_bf16 v[32:35], v[190:193], v[206:209], v[32:35]
	v_mfma_f32_16x16x32_bf16 v[20:23], v[170:173], v[214:217], v[20:23]
	v_mfma_f32_16x16x32_bf16 v[16:19], v[190:193], v[214:217], v[16:19]
	v_mfma_f32_16x16x32_bf16 v[8:11], v[170:173], v[222:225], v[8:11]
	v_mfma_f32_16x16x32_bf16 v[0:3], v[190:193], v[222:225], v[0:3]
	v_mfma_f32_16x16x32_bf16 v[52:55], v[186:189], v[202:205], v[52:55]
	v_mfma_f32_16x16x32_bf16 v[48:51], v[194:197], v[202:205], v[48:51]
	v_mfma_f32_16x16x32_bf16 v[36:39], v[186:189], v[210:213], v[36:39]
	v_mfma_f32_16x16x32_bf16 v[32:35], v[194:197], v[210:213], v[32:35]
	v_mfma_f32_16x16x32_bf16 v[20:23], v[186:189], v[218:221], v[20:23]
	v_mfma_f32_16x16x32_bf16 v[16:19], v[194:197], v[218:221], v[16:19]
	v_mfma_f32_16x16x32_bf16 v[8:11], v[186:189], v[226:229], v[8:11]
	v_mfma_f32_16x16x32_bf16 v[0:3], v[194:197], v[226:229], v[0:3]
	s_setprio 0
	s_barrier
	s_setprio 2
	s_add_i32 s53, s53, 2
	s_add_u32 s14, s14, 0x100
	s_addc_u32 s15, s15, 0
	s_add_u32 s51, s51, 0x100
	s_addc_u32 s52, s52, 0
	s_cmp_gt_u32 s53, 13
	s_cbranch_scc0 .LBB0_271
	s_and_b64 vcc, exec, s[12:13]
	s_cbranch_vccz .LBB0_274
	s_barrier

.LBB0_361:
	s_add_u32 s34, s30, 0xfffc0080
	s_addc_u32 s35, s31, -1
	s_add_i32 s62, 0, 0x10000
	s_cmp_eq_u32 s61, 12
	s_cselect_b32 s37, s25, s35
	s_cselect_b32 s36, s57, s34
	v_add_u32_e32 v96, s62, v151
	s_cselect_b32 s35, s15, s60
	s_cselect_b32 s34, s58, s59
	s_add_i32 s64, 0, 0x14000
	ds_read_b128 v[164:167], v96
	ds_read_b128 v[168:171], v96 offset:1024
	ds_read_b128 v[186:189], v96 offset:2048
	ds_read_b128 v[190:193], v96 offset:3072
	v_add_u32_e32 v96, s64, v151
	ds_read_b128 v[194:197], v96
	ds_read_b128 v[198:201], v96 offset:1024
	ds_read_b128 v[202:205], v96 offset:2048
	ds_read_b128 v[206:209], v96 offset:3072
	v_lshl_add_u64 v[154:155], s[30:31], 0, v[146:147]
	s_add_i32 m0, s43, 0xc000
	ds_read_b128 v[210:213], v162
	ds_read_b128 v[214:217], v162 offset:1024
	ds_read_b128 v[218:221], v162 offset:2048
	ds_read_b128 v[222:225], v162 offset:3072
	ds_read_b128 v[226:229], v162 offset:4096
	ds_read_b128 v[230:233], v162 offset:5120
	ds_read_b128 v[242:245], v162 offset:6144
	ds_read_b128 v[246:249], v162 offset:7168
	global_load_lds_dwordx4 v[154:155], off
	v_lshl_add_u64 v[154:155], s[30:31], 0, v[148:149]
	s_add_i32 m0, s43, 0xe000
	s_nop 0
	global_load_lds_dwordx4 v[154:155], off
	s_setprio 1
	s_waitcnt vmcnt(8) lgkmcnt(0)
	s_barrier
	v_mfma_f32_16x16x32_bf16 v[126:129], v[164:167], v[210:213], v[126:129]
	v_mfma_f32_16x16x32_bf16 v[122:125], v[186:189], v[210:213], v[122:125]
	v_mfma_f32_16x16x32_bf16 v[118:121], v[164:167], v[218:221], v[118:121]
	v_mfma_f32_16x16x32_bf16 v[114:117], v[186:189], v[218:221], v[114:117]
	v_mfma_f32_16x16x32_bf16 v[110:113], v[164:167], v[226:229], v[110:113]
	v_mfma_f32_16x16x32_bf16 v[106:109], v[186:189], v[226:229], v[106:109]
	v_mfma_f32_16x16x32_bf16 v[102:105], v[164:167], v[242:245], v[102:105]
	v_mfma_f32_16x16x32_bf16 v[98:101], v[186:189], v[242:245], v[98:101]
	v_mfma_f32_16x16x32_bf16 v[126:129], v[168:171], v[214:217], v[126:129]
	v_mfma_f32_16x16x32_bf16 v[122:125], v[190:193], v[214:217], v[122:125]
	v_mfma_f32_16x16x32_bf16 v[118:121], v[168:171], v[222:225], v[118:121]
	v_mfma_f32_16x16x32_bf16 v[114:117], v[190:193], v[222:225], v[114:117]
	v_mfma_f32_16x16x32_bf16 v[110:113], v[168:171], v[230:233], v[110:113]
	v_mfma_f32_16x16x32_bf16 v[106:109], v[190:193], v[230:233], v[106:109]
	v_mfma_f32_16x16x32_bf16 v[102:105], v[168:171], v[246:249], v[102:105]
	v_mfma_f32_16x16x32_bf16 v[98:101], v[190:193], v[246:249], v[98:101]
	s_setprio 0
	s_setprio 1
	v_mfma_f32_16x16x32_bf16 v[76:79], v[194:197], v[210:213], v[76:79]
	v_mfma_f32_16x16x32_bf16 v[64:67], v[202:205], v[210:213], v[64:67]
	v_mfma_f32_16x16x32_bf16 v[60:63], v[194:197], v[218:221], v[60:63]
	v_mfma_f32_16x16x32_bf16 v[52:55], v[202:205], v[218:221], v[52:55]
	v_mfma_f32_16x16x32_bf16 v[44:47], v[194:197], v[226:229], v[44:47]
	v_mfma_f32_16x16x32_bf16 v[40:43], v[202:205], v[226:229], v[40:43]
	v_mfma_f32_16x16x32_bf16 v[36:39], v[194:197], v[242:245], v[36:39]
	v_mfma_f32_16x16x32_bf16 v[32:35], v[202:205], v[242:245], v[32:35]
	v_mfma_f32_16x16x32_bf16 v[76:79], v[198:201], v[214:217], v[76:79]
	v_mfma_f32_16x16x32_bf16 v[64:67], v[206:209], v[214:217], v[64:67]
	v_mfma_f32_16x16x32_bf16 v[60:63], v[198:201], v[222:225], v[60:63]
	v_mfma_f32_16x16x32_bf16 v[52:55], v[206:209], v[222:225], v[52:55]
	v_mfma_f32_16x16x32_bf16 v[44:47], v[198:201], v[230:233], v[44:47]
	v_mfma_f32_16x16x32_bf16 v[40:43], v[206:209], v[230:233], v[40:43]
	v_mfma_f32_16x16x32_bf16 v[36:39], v[198:201], v[246:249], v[36:39]
	v_mfma_f32_16x16x32_bf16 v[32:35], v[206:209], v[246:249], v[32:35]
	s_setprio 0
	s_barrier
	s_setprio 2
	s_add_i32 s62, s62, s40
	v_lshl_add_u64 v[154:155], s[34:35], 0, v[134:135]
	s_mov_b32 m0, s62
	ds_read_b128 v[210:213], v162 offset:16384
	ds_read_b128 v[214:217], v162 offset:17408
	ds_read_b128 v[218:221], v162 offset:18432
	ds_read_b128 v[222:225], v162 offset:19456
	ds_read_b128 v[226:229], v162 offset:20480
	ds_read_b128 v[230:233], v162 offset:21504
	ds_read_b128 v[242:245], v162 offset:22528
	ds_read_b128 v[246:249], v162 offset:23552
	global_load_lds_dwordx4 v[154:155], off
	s_add_i32 m0, s62, 0x2000
	s_add_u32 s62, s34, 0x40000
	v_lshl_add_u64 v[156:157], s[34:35], 0, v[130:131]
	s_addc_u32 s63, s35, 0
	s_add_i32 s64, s64, s40
	global_load_lds_dwordx4 v[156:157], off
	v_lshl_add_u64 v[158:159], s[62:63], 0, v[134:135]
	s_mov_b32 m0, s64
	v_lshl_add_u64 v[172:173], s[36:37], 0, v[132:133]
	global_load_lds_dwordx4 v[158:159], off
	v_lshl_add_u64 v[158:159], s[62:63], 0, v[130:131]
	s_add_i32 m0, s64, 0x2000
	s_nop 0
	global_load_lds_dwordx4 v[158:159], off
	v_lshl_add_u64 v[158:159], s[36:37], 0, v[136:137]
	s_mov_b32 m0, s43
	s_nop 0
	global_load_lds_dwordx4 v[158:159], off
	s_mov_b32 m0, s44
	s_nop 0
	global_load_lds_dwordx4 v[172:173], off
	s_setprio 1
	s_waitcnt vmcnt(8) lgkmcnt(0)
	s_barrier
	v_mfma_f32_16x16x32_bf16 v[92:95], v[164:167], v[210:213], v[92:95]
	v_mfma_f32_16x16x32_bf16 v[88:91], v[186:189], v[210:213], v[88:91]
	v_mfma_f32_16x16x32_bf16 v[84:87], v[164:167], v[218:221], v[84:87]
	v_mfma_f32_16x16x32_bf16 v[80:83], v[186:189], v[218:221], v[80:83]
	v_mfma_f32_16x16x32_bf16 v[72:75], v[164:167], v[226:229], v[72:75]
	v_mfma_f32_16x16x32_bf16 v[68:71], v[186:189], v[226:229], v[68:71]
	v_mfma_f32_16x16x32_bf16 v[56:59], v[164:167], v[242:245], v[56:59]
	v_mfma_f32_16x16x32_bf16 v[48:51], v[186:189], v[242:245], v[48:51]
	v_mfma_f32_16x16x32_bf16 v[92:95], v[168:171], v[214:217], v[92:95]
	v_mfma_f32_16x16x32_bf16 v[88:91], v[190:193], v[214:217], v[88:91]
	v_mfma_f32_16x16x32_bf16 v[84:87], v[168:171], v[222:225], v[84:87]
	v_mfma_f32_16x16x32_bf16 v[80:83], v[190:193], v[222:225], v[80:83]
	v_mfma_f32_16x16x32_bf16 v[72:75], v[168:171], v[230:233], v[72:75]
	v_mfma_f32_16x16x32_bf16 v[68:71], v[190:193], v[230:233], v[68:71]
	v_mfma_f32_16x16x32_bf16 v[56:59], v[168:171], v[246:249], v[56:59]
	v_mfma_f32_16x16x32_bf16 v[48:51], v[190:193], v[246:249], v[48:51]
	s_setprio 0
	s_setprio 1
	v_mfma_f32_16x16x32_bf16 v[28:31], v[194:197], v[210:213], v[28:31]
	v_mfma_f32_16x16x32_bf16 v[24:27], v[202:205], v[210:213], v[24:27]
	v_mfma_f32_16x16x32_bf16 v[20:23], v[194:197], v[218:221], v[20:23]
	v_mfma_f32_16x16x32_bf16 v[16:19], v[202:205], v[218:221], v[16:19]
	v_mfma_f32_16x16x32_bf16 v[12:15], v[194:197], v[226:229], v[12:15]
	v_mfma_f32_16x16x32_bf16 v[8:11], v[202:205], v[226:229], v[8:11]
	v_mfma_f32_16x16x32_bf16 v[4:7], v[194:197], v[242:245], v[4:7]
	v_mfma_f32_16x16x32_bf16 v[0:3], v[202:205], v[242:245], v[0:3]
	v_mfma_f32_16x16x32_bf16 v[28:31], v[198:201], v[214:217], v[28:31]
	v_mfma_f32_16x16x32_bf16 v[24:27], v[206:209], v[214:217], v[24:27]
	v_mfma_f32_16x16x32_bf16 v[20:23], v[198:201], v[222:225], v[20:23]
	v_mfma_f32_16x16x32_bf16 v[16:19], v[206:209], v[222:225], v[16:19]
	v_mfma_f32_16x16x32_bf16 v[12:15], v[198:201], v[230:233], v[12:15]
	v_mfma_f32_16x16x32_bf16 v[8:11], v[206:209], v[230:233], v[8:11]
	v_mfma_f32_16x16x32_bf16 v[4:7], v[198:201], v[246:249], v[4:7]
	v_mfma_f32_16x16x32_bf16 v[0:3], v[206:209], v[246:249], v[0:3]
	s_setprio 0
	s_barrier
	s_setprio 2
	s_add_i32 s62, 0, 0x18000
	v_add_u32_e32 v96, s62, v151
	s_add_i32 s63, 0, 0x1c000
	ds_read_b128 v[164:167], v96
	ds_read_b128 v[168:171], v96 offset:1024
	ds_read_b128 v[186:189], v96 offset:2048
	ds_read_b128 v[190:193], v96 offset:3072
	v_add_u32_e32 v96, s63, v151
	ds_read_b128 v[194:197], v96
	ds_read_b128 v[198:201], v96 offset:1024
	ds_read_b128 v[202:205], v96 offset:2048
	ds_read_b128 v[206:209], v96 offset:3072
	s_add_u32 s36, s36, 0x40000
	s_addc_u32 s37, s37, 0
	s_mov_b32 m0, s45
	v_lshl_add_u64 v[182:183], s[36:37], 0, v[136:137]
	ds_read_b128 v[210:213], v162 offset:32768
	ds_read_b128 v[214:217], v162 offset:33792
	ds_read_b128 v[218:221], v162 offset:34816
	ds_read_b128 v[222:225], v162 offset:35840
	ds_read_b128 v[226:229], v162 offset:36864
	ds_read_b128 v[230:233], v162 offset:37888
	ds_read_b128 v[242:245], v162 offset:38912
	ds_read_b128 v[246:249], v162 offset:39936
	global_load_lds_dwordx4 v[182:183], off
	v_lshl_add_u64 v[182:183], s[36:37], 0, v[132:133]
	s_mov_b32 m0, s46
	s_nop 0
	global_load_lds_dwordx4 v[182:183], off
	s_setprio 1
	s_waitcnt vmcnt(8) lgkmcnt(0)
	s_barrier
	v_mfma_f32_16x16x32_bf16 v[126:129], v[164:167], v[210:213], v[126:129]
	v_mfma_f32_16x16x32_bf16 v[122:125], v[186:189], v[210:213], v[122:125]
	v_mfma_f32_16x16x32_bf16 v[118:121], v[164:167], v[218:221], v[118:121]
	v_mfma_f32_16x16x32_bf16 v[114:117], v[186:189], v[218:221], v[114:117]
	v_mfma_f32_16x16x32_bf16 v[110:113], v[164:167], v[226:229], v[110:113]
	v_mfma_f32_16x16x32_bf16 v[106:109], v[186:189], v[226:229], v[106:109]
	v_mfma_f32_16x16x32_bf16 v[102:105], v[164:167], v[242:245], v[102:105]
	v_mfma_f32_16x16x32_bf16 v[98:101], v[186:189], v[242:245], v[98:101]
	v_mfma_f32_16x16x32_bf16 v[126:129], v[168:171], v[214:217], v[126:129]
	v_mfma_f32_16x16x32_bf16 v[122:125], v[190:193], v[214:217], v[122:125]
	v_mfma_f32_16x16x32_bf16 v[118:121], v[168:171], v[222:225], v[118:121]
	v_mfma_f32_16x16x32_bf16 v[114:117], v[190:193], v[222:225], v[114:117]
	v_mfma_f32_16x16x32_bf16 v[110:113], v[168:171], v[230:233], v[110:113]
	v_mfma_f32_16x16x32_bf16 v[106:109], v[190:193], v[230:233], v[106:109]
	v_mfma_f32_16x16x32_bf16 v[102:105], v[168:171], v[246:249], v[102:105]
	v_mfma_f32_16x16x32_bf16 v[98:101], v[190:193], v[246:249], v[98:101]
	s_setprio 0
	s_setprio 1
	v_mfma_f32_16x16x32_bf16 v[76:79], v[194:197], v[210:213], v[76:79]
	v_mfma_f32_16x16x32_bf16 v[64:67], v[202:205], v[210:213], v[64:67]
	v_mfma_f32_16x16x32_bf16 v[60:63], v[194:197], v[218:221], v[60:63]
	v_mfma_f32_16x16x32_bf16 v[52:55], v[202:205], v[218:221], v[52:55]
	v_mfma_f32_16x16x32_bf16 v[44:47], v[194:197], v[226:229], v[44:47]
	v_mfma_f32_16x16x32_bf16 v[40:43], v[202:205], v[226:229], v[40:43]
	v_mfma_f32_16x16x32_bf16 v[36:39], v[194:197], v[242:245], v[36:39]
	v_mfma_f32_16x16x32_bf16 v[32:35], v[202:205], v[242:245], v[32:35]
	v_mfma_f32_16x16x32_bf16 v[76:79], v[198:201], v[214:217], v[76:79]
	v_mfma_f32_16x16x32_bf16 v[64:67], v[206:209], v[214:217], v[64:67]
	v_mfma_f32_16x16x32_bf16 v[60:63], v[198:201], v[222:225], v[60:63]
	v_mfma_f32_16x16x32_bf16 v[52:55], v[206:209], v[222:225], v[52:55]
	v_mfma_f32_16x16x32_bf16 v[44:47], v[198:201], v[230:233], v[44:47]
	v_mfma_f32_16x16x32_bf16 v[40:43], v[206:209], v[230:233], v[40:43]
	v_mfma_f32_16x16x32_bf16 v[36:39], v[198:201], v[246:249], v[36:39]
	v_mfma_f32_16x16x32_bf16 v[32:35], v[206:209], v[246:249], v[32:35]
	s_setprio 0
	s_barrier
	s_setprio 2
	s_add_i32 s36, s62, s40
	v_lshl_add_u64 v[154:155], v[154:155], 0, s[16:17]
	s_mov_b32 m0, s36
	ds_read_b128 v[210:213], v162 offset:49152
	ds_read_b128 v[214:217], v162 offset:50176
	ds_read_b128 v[218:221], v162 offset:51200
	ds_read_b128 v[222:225], v162 offset:52224
	ds_read_b128 v[226:229], v162 offset:53248
	ds_read_b128 v[230:233], v162 offset:54272
	ds_read_b128 v[242:245], v162 offset:55296
	ds_read_b128 v[246:249], v162 offset:56320
	global_load_lds_dwordx4 v[154:155], off
	s_add_i32 m0, s36, 0x2000
	s_add_u32 s34, s34, 0x40080
	v_lshl_add_u64 v[154:155], v[156:157], 0, s[16:17]
	s_addc_u32 s35, s35, 0
	s_add_i32 s36, s63, s40
	global_load_lds_dwordx4 v[154:155], off
	v_lshl_add_u64 v[154:155], s[34:35], 0, v[134:135]
	s_mov_b32 m0, s36
	s_nop 0
	global_load_lds_dwordx4 v[154:155], off
	v_lshl_add_u64 v[154:155], s[34:35], 0, v[130:131]
	s_add_i32 m0, s36, 0x2000
	s_nop 0
	global_load_lds_dwordx4 v[154:155], off
	v_lshl_add_u64 v[154:155], v[158:159], 0, s[16:17]
	s_mov_b32 m0, s50
	s_nop 0
	global_load_lds_dwordx4 v[154:155], off
	v_lshl_add_u64 v[154:155], v[172:173], 0, s[16:17]
	s_mov_b32 m0, s51
	s_nop 0
	global_load_lds_dwordx4 v[154:155], off
	s_setprio 1
	s_waitcnt vmcnt(8) lgkmcnt(0)
	s_barrier
	v_mfma_f32_16x16x32_bf16 v[92:95], v[164:167], v[210:213], v[92:95]
	v_mfma_f32_16x16x32_bf16 v[88:91], v[186:189], v[210:213], v[88:91]
	v_mfma_f32_16x16x32_bf16 v[84:87], v[164:167], v[218:221], v[84:87]
	v_mfma_f32_16x16x32_bf16 v[80:83], v[186:189], v[218:221], v[80:83]
	v_mfma_f32_16x16x32_bf16 v[72:75], v[164:167], v[226:229], v[72:75]
	v_mfma_f32_16x16x32_bf16 v[68:71], v[186:189], v[226:229], v[68:71]
	v_mfma_f32_16x16x32_bf16 v[56:59], v[164:167], v[242:245], v[56:59]
	v_mfma_f32_16x16x32_bf16 v[48:51], v[186:189], v[242:245], v[48:51]
	v_mfma_f32_16x16x32_bf16 v[92:95], v[168:171], v[214:217], v[92:95]
	v_mfma_f32_16x16x32_bf16 v[88:91], v[190:193], v[214:217], v[88:91]
	v_mfma_f32_16x16x32_bf16 v[84:87], v[168:171], v[222:225], v[84:87]
	v_mfma_f32_16x16x32_bf16 v[80:83], v[190:193], v[222:225], v[80:83]
	v_mfma_f32_16x16x32_bf16 v[72:75], v[168:171], v[230:233], v[72:75]
	v_mfma_f32_16x16x32_bf16 v[68:71], v[190:193], v[230:233], v[68:71]
	v_mfma_f32_16x16x32_bf16 v[56:59], v[168:171], v[246:249], v[56:59]
	v_mfma_f32_16x16x32_bf16 v[48:51], v[190:193], v[246:249], v[48:51]
	s_setprio 0
	s_setprio 1
	v_mfma_f32_16x16x32_bf16 v[28:31], v[194:197], v[210:213], v[28:31]
	v_mfma_f32_16x16x32_bf16 v[24:27], v[202:205], v[210:213], v[24:27]
	v_mfma_f32_16x16x32_bf16 v[20:23], v[194:197], v[218:221], v[20:23]
	v_mfma_f32_16x16x32_bf16 v[16:19], v[202:205], v[218:221], v[16:19]
	v_mfma_f32_16x16x32_bf16 v[12:15], v[194:197], v[226:229], v[12:15]
	v_mfma_f32_16x16x32_bf16 v[8:11], v[202:205], v[226:229], v[8:11]
	v_mfma_f32_16x16x32_bf16 v[4:7], v[194:197], v[242:245], v[4:7]
	v_mfma_f32_16x16x32_bf16 v[0:3], v[202:205], v[242:245], v[0:3]
	v_mfma_f32_16x16x32_bf16 v[28:31], v[198:201], v[214:217], v[28:31]
	v_mfma_f32_16x16x32_bf16 v[24:27], v[206:209], v[214:217], v[24:27]
	v_mfma_f32_16x16x32_bf16 v[20:23], v[198:201], v[222:225], v[20:23]
	v_mfma_f32_16x16x32_bf16 v[16:19], v[206:209], v[222:225], v[16:19]
	v_mfma_f32_16x16x32_bf16 v[12:15], v[198:201], v[230:233], v[12:15]
	v_mfma_f32_16x16x32_bf16 v[8:11], v[206:209], v[230:233], v[8:11]
	v_mfma_f32_16x16x32_bf16 v[4:7], v[198:201], v[246:249], v[4:7]
	v_mfma_f32_16x16x32_bf16 v[0:3], v[206:209], v[246:249], v[0:3]
	s_setprio 0
	s_barrier
	s_setprio 2
	s_add_i32 s61, s61, 2
	s_add_u32 s30, s30, 0x100
	s_addc_u32 s31, s31, 0
	s_add_u32 s59, s59, 0x100
	s_addc_u32 s60, s60, 0
	s_cmp_gt_u32 s61, 13
	s_cbranch_scc0 .LBB0_361
	s_and_b64 vcc, exec, s[20:21]
	s_cbranch_vccz .LBB0_364
	s_barrier

.LBB0_393:
	s_add_u32 s26, s14, 0xfffc0080
	s_addc_u32 s27, s15, -1
	s_add_i32 s57, 0, 0x10000
	s_cmp_eq_u32 s56, 12
	s_cselect_b32 s29, s19, s27
	s_cselect_b32 s28, s52, s26
	v_add_u32_e32 v151, s57, v141
	s_cselect_b32 s27, s5, s55
	s_cselect_b32 s26, s53, s54
	s_add_i32 s60, 0, 0x14000
	ds_read_b128 v[162:165], v151
	ds_read_b128 v[166:169], v151 offset:1024
	ds_read_b128 v[170:173], v151 offset:2048
	ds_read_b128 v[186:189], v151 offset:3072
	v_add_u32_e32 v151, s60, v141
	ds_read_b128 v[190:193], v151
	ds_read_b128 v[194:197], v151 offset:1024
	ds_read_b128 v[198:201], v151 offset:2048
	ds_read_b128 v[202:205], v151 offset:3072
	v_lshl_add_u64 v[152:153], s[14:15], 0, v[146:147]
	s_add_i32 m0, s39, 0xc000
	ds_read_b128 v[206:209], v150
	ds_read_b128 v[210:213], v150 offset:1024
	ds_read_b128 v[214:217], v150 offset:2048
	ds_read_b128 v[218:221], v150 offset:3072
	ds_read_b128 v[222:225], v150 offset:4096
	ds_read_b128 v[226:229], v150 offset:5120
	ds_read_b128 v[230:233], v150 offset:6144
	ds_read_b128 v[242:245], v150 offset:7168
	global_load_lds_dwordx4 v[152:153], off
	v_lshl_add_u64 v[152:153], s[14:15], 0, v[148:149]
	s_add_i32 m0, s39, 0xe000
	s_nop 0
	global_load_lds_dwordx4 v[152:153], off
	s_setprio 1
	s_waitcnt vmcnt(8) lgkmcnt(0)
	s_barrier
	v_mfma_f32_16x16x32_bf16 v[126:129], v[162:165], v[206:209], v[126:129]
	v_mfma_f32_16x16x32_bf16 v[122:125], v[170:173], v[206:209], v[122:125]
	v_mfma_f32_16x16x32_bf16 v[118:121], v[162:165], v[214:217], v[118:121]
	v_mfma_f32_16x16x32_bf16 v[114:117], v[170:173], v[214:217], v[114:117]
	v_mfma_f32_16x16x32_bf16 v[110:113], v[162:165], v[222:225], v[110:113]
	v_mfma_f32_16x16x32_bf16 v[106:109], v[170:173], v[222:225], v[106:109]
	v_mfma_f32_16x16x32_bf16 v[102:105], v[162:165], v[230:233], v[102:105]
	v_mfma_f32_16x16x32_bf16 v[98:101], v[170:173], v[230:233], v[98:101]
	v_mfma_f32_16x16x32_bf16 v[126:129], v[166:169], v[210:213], v[126:129]
	v_mfma_f32_16x16x32_bf16 v[122:125], v[186:189], v[210:213], v[122:125]
	v_mfma_f32_16x16x32_bf16 v[118:121], v[166:169], v[218:221], v[118:121]
	v_mfma_f32_16x16x32_bf16 v[114:117], v[186:189], v[218:221], v[114:117]
	v_mfma_f32_16x16x32_bf16 v[110:113], v[166:169], v[226:229], v[110:113]
	v_mfma_f32_16x16x32_bf16 v[106:109], v[186:189], v[226:229], v[106:109]
	v_mfma_f32_16x16x32_bf16 v[102:105], v[166:169], v[242:245], v[102:105]
	v_mfma_f32_16x16x32_bf16 v[98:101], v[186:189], v[242:245], v[98:101]
	s_setprio 0
	s_setprio 1
	v_mfma_f32_16x16x32_bf16 v[68:71], v[190:193], v[206:209], v[68:71]
	v_mfma_f32_16x16x32_bf16 v[64:67], v[198:201], v[206:209], v[64:67]
	v_mfma_f32_16x16x32_bf16 v[52:55], v[190:193], v[214:217], v[52:55]
	v_mfma_f32_16x16x32_bf16 v[48:51], v[198:201], v[214:217], v[48:51]
	v_mfma_f32_16x16x32_bf16 v[44:47], v[190:193], v[222:225], v[44:47]
	v_mfma_f32_16x16x32_bf16 v[40:43], v[198:201], v[222:225], v[40:43]
	v_mfma_f32_16x16x32_bf16 v[36:39], v[190:193], v[230:233], v[36:39]
	v_mfma_f32_16x16x32_bf16 v[32:35], v[198:201], v[230:233], v[32:35]
	v_mfma_f32_16x16x32_bf16 v[68:71], v[194:197], v[210:213], v[68:71]
	v_mfma_f32_16x16x32_bf16 v[64:67], v[202:205], v[210:213], v[64:67]
	v_mfma_f32_16x16x32_bf16 v[52:55], v[194:197], v[218:221], v[52:55]
	v_mfma_f32_16x16x32_bf16 v[48:51], v[202:205], v[218:221], v[48:51]
	v_mfma_f32_16x16x32_bf16 v[44:47], v[194:197], v[226:229], v[44:47]
	v_mfma_f32_16x16x32_bf16 v[40:43], v[202:205], v[226:229], v[40:43]
	v_mfma_f32_16x16x32_bf16 v[36:39], v[194:197], v[242:245], v[36:39]
	v_mfma_f32_16x16x32_bf16 v[32:35], v[202:205], v[242:245], v[32:35]
	s_setprio 0
	s_barrier
	s_setprio 2
	s_add_i32 s57, s57, s36
	v_lshl_add_u64 v[152:153], s[26:27], 0, v[96:97]
	s_mov_b32 m0, s57
	ds_read_b128 v[206:209], v150 offset:16384
	ds_read_b128 v[210:213], v150 offset:17408
	ds_read_b128 v[214:217], v150 offset:18432
	ds_read_b128 v[218:221], v150 offset:19456
	ds_read_b128 v[222:225], v150 offset:20480
	ds_read_b128 v[226:229], v150 offset:21504
	ds_read_b128 v[230:233], v150 offset:22528
	ds_read_b128 v[242:245], v150 offset:23552
	global_load_lds_dwordx4 v[152:153], off
	s_add_i32 m0, s57, 0x2000
	s_add_u32 s58, s26, 0x40000
	v_lshl_add_u64 v[154:155], s[26:27], 0, v[130:131]
	s_addc_u32 s59, s27, 0
	s_add_i32 s57, s60, s36
	global_load_lds_dwordx4 v[154:155], off
	v_lshl_add_u64 v[156:157], s[58:59], 0, v[96:97]
	s_mov_b32 m0, s57
	v_lshl_add_u64 v[158:159], s[28:29], 0, v[132:133]
	global_load_lds_dwordx4 v[156:157], off
	v_lshl_add_u64 v[156:157], s[58:59], 0, v[130:131]
	s_add_i32 m0, s57, 0x2000
	s_nop 0
	global_load_lds_dwordx4 v[156:157], off
	v_lshl_add_u64 v[156:157], s[28:29], 0, v[134:135]
	s_mov_b32 m0, s39
	s_nop 0
	global_load_lds_dwordx4 v[156:157], off
	s_mov_b32 m0, s40
	s_nop 0
	global_load_lds_dwordx4 v[158:159], off
	s_setprio 1
	s_waitcnt vmcnt(8) lgkmcnt(0)
	s_barrier
	v_mfma_f32_16x16x32_bf16 v[92:95], v[162:165], v[206:209], v[92:95]
	v_mfma_f32_16x16x32_bf16 v[88:91], v[170:173], v[206:209], v[88:91]
	v_mfma_f32_16x16x32_bf16 v[84:87], v[162:165], v[214:217], v[84:87]
	v_mfma_f32_16x16x32_bf16 v[80:83], v[170:173], v[214:217], v[80:83]
	v_mfma_f32_16x16x32_bf16 v[76:79], v[162:165], v[222:225], v[76:79]
	v_mfma_f32_16x16x32_bf16 v[72:75], v[170:173], v[222:225], v[72:75]
	v_mfma_f32_16x16x32_bf16 v[60:63], v[162:165], v[230:233], v[60:63]
	v_mfma_f32_16x16x32_bf16 v[56:59], v[170:173], v[230:233], v[56:59]
	v_mfma_f32_16x16x32_bf16 v[92:95], v[166:169], v[210:213], v[92:95]
	v_mfma_f32_16x16x32_bf16 v[88:91], v[186:189], v[210:213], v[88:91]
	v_mfma_f32_16x16x32_bf16 v[84:87], v[166:169], v[218:221], v[84:87]
	v_mfma_f32_16x16x32_bf16 v[80:83], v[186:189], v[218:221], v[80:83]
	v_mfma_f32_16x16x32_bf16 v[76:79], v[166:169], v[226:229], v[76:79]
	v_mfma_f32_16x16x32_bf16 v[72:75], v[186:189], v[226:229], v[72:75]
	v_mfma_f32_16x16x32_bf16 v[60:63], v[166:169], v[242:245], v[60:63]
	v_mfma_f32_16x16x32_bf16 v[56:59], v[186:189], v[242:245], v[56:59]
	s_setprio 0
	s_setprio 1
	v_mfma_f32_16x16x32_bf16 v[28:31], v[190:193], v[206:209], v[28:31]
	v_mfma_f32_16x16x32_bf16 v[24:27], v[198:201], v[206:209], v[24:27]
	v_mfma_f32_16x16x32_bf16 v[20:23], v[190:193], v[214:217], v[20:23]
	v_mfma_f32_16x16x32_bf16 v[16:19], v[198:201], v[214:217], v[16:19]
	v_mfma_f32_16x16x32_bf16 v[12:15], v[190:193], v[222:225], v[12:15]
	v_mfma_f32_16x16x32_bf16 v[8:11], v[198:201], v[222:225], v[8:11]
	v_mfma_f32_16x16x32_bf16 v[4:7], v[190:193], v[230:233], v[4:7]
	v_mfma_f32_16x16x32_bf16 v[0:3], v[198:201], v[230:233], v[0:3]
	v_mfma_f32_16x16x32_bf16 v[28:31], v[194:197], v[210:213], v[28:31]
	v_mfma_f32_16x16x32_bf16 v[24:27], v[202:205], v[210:213], v[24:27]
	v_mfma_f32_16x16x32_bf16 v[20:23], v[194:197], v[218:221], v[20:23]
	v_mfma_f32_16x16x32_bf16 v[16:19], v[202:205], v[218:221], v[16:19]
	v_mfma_f32_16x16x32_bf16 v[12:15], v[194:197], v[226:229], v[12:15]
	v_mfma_f32_16x16x32_bf16 v[8:11], v[202:205], v[226:229], v[8:11]
	v_mfma_f32_16x16x32_bf16 v[4:7], v[194:197], v[242:245], v[4:7]
	v_mfma_f32_16x16x32_bf16 v[0:3], v[202:205], v[242:245], v[0:3]
	s_setprio 0
	s_barrier
	s_setprio 2
	s_add_i32 s57, 0, 0x18000
	v_add_u32_e32 v151, s57, v141
	s_add_i32 s58, 0, 0x1c000
	ds_read_b128 v[162:165], v151
	ds_read_b128 v[166:169], v151 offset:1024
	ds_read_b128 v[170:173], v151 offset:2048
	ds_read_b128 v[186:189], v151 offset:3072
	v_add_u32_e32 v151, s58, v141
	ds_read_b128 v[190:193], v151
	ds_read_b128 v[194:197], v151 offset:1024
	ds_read_b128 v[198:201], v151 offset:2048
	ds_read_b128 v[202:205], v151 offset:3072
	s_add_u32 s28, s28, 0x40000
	s_addc_u32 s29, s29, 0
	s_mov_b32 m0, s41
	v_lshl_add_u64 v[182:183], s[28:29], 0, v[134:135]
	ds_read_b128 v[206:209], v150 offset:32768
	ds_read_b128 v[210:213], v150 offset:33792
	ds_read_b128 v[214:217], v150 offset:34816
	ds_read_b128 v[218:221], v150 offset:35840
	ds_read_b128 v[222:225], v150 offset:36864
	ds_read_b128 v[226:229], v150 offset:37888
	ds_read_b128 v[230:233], v150 offset:38912
	ds_read_b128 v[242:245], v150 offset:39936
	global_load_lds_dwordx4 v[182:183], off
	v_lshl_add_u64 v[182:183], s[28:29], 0, v[132:133]
	s_mov_b32 m0, s42
	s_nop 0
	global_load_lds_dwordx4 v[182:183], off
	s_setprio 1
	s_waitcnt vmcnt(8) lgkmcnt(0)
	s_barrier
	v_mfma_f32_16x16x32_bf16 v[126:129], v[162:165], v[206:209], v[126:129]
	v_mfma_f32_16x16x32_bf16 v[122:125], v[170:173], v[206:209], v[122:125]
	v_mfma_f32_16x16x32_bf16 v[118:121], v[162:165], v[214:217], v[118:121]
	v_mfma_f32_16x16x32_bf16 v[114:117], v[170:173], v[214:217], v[114:117]
	v_mfma_f32_16x16x32_bf16 v[110:113], v[162:165], v[222:225], v[110:113]
	v_mfma_f32_16x16x32_bf16 v[106:109], v[170:173], v[222:225], v[106:109]
	v_mfma_f32_16x16x32_bf16 v[102:105], v[162:165], v[230:233], v[102:105]
	v_mfma_f32_16x16x32_bf16 v[98:101], v[170:173], v[230:233], v[98:101]
	v_mfma_f32_16x16x32_bf16 v[126:129], v[166:169], v[210:213], v[126:129]
	v_mfma_f32_16x16x32_bf16 v[122:125], v[186:189], v[210:213], v[122:125]
	v_mfma_f32_16x16x32_bf16 v[118:121], v[166:169], v[218:221], v[118:121]
	v_mfma_f32_16x16x32_bf16 v[114:117], v[186:189], v[218:221], v[114:117]
	v_mfma_f32_16x16x32_bf16 v[110:113], v[166:169], v[226:229], v[110:113]
	v_mfma_f32_16x16x32_bf16 v[106:109], v[186:189], v[226:229], v[106:109]
	v_mfma_f32_16x16x32_bf16 v[102:105], v[166:169], v[242:245], v[102:105]
	v_mfma_f32_16x16x32_bf16 v[98:101], v[186:189], v[242:245], v[98:101]
	s_setprio 0
	s_setprio 1
	v_mfma_f32_16x16x32_bf16 v[68:71], v[190:193], v[206:209], v[68:71]
	v_mfma_f32_16x16x32_bf16 v[64:67], v[198:201], v[206:209], v[64:67]
	v_mfma_f32_16x16x32_bf16 v[52:55], v[190:193], v[214:217], v[52:55]
	v_mfma_f32_16x16x32_bf16 v[48:51], v[198:201], v[214:217], v[48:51]
	v_mfma_f32_16x16x32_bf16 v[44:47], v[190:193], v[222:225], v[44:47]
	v_mfma_f32_16x16x32_bf16 v[40:43], v[198:201], v[222:225], v[40:43]
	v_mfma_f32_16x16x32_bf16 v[36:39], v[190:193], v[230:233], v[36:39]
	v_mfma_f32_16x16x32_bf16 v[32:35], v[198:201], v[230:233], v[32:35]
	v_mfma_f32_16x16x32_bf16 v[68:71], v[194:197], v[210:213], v[68:71]
	v_mfma_f32_16x16x32_bf16 v[64:67], v[202:205], v[210:213], v[64:67]
	v_mfma_f32_16x16x32_bf16 v[52:55], v[194:197], v[218:221], v[52:55]
	v_mfma_f32_16x16x32_bf16 v[48:51], v[202:205], v[218:221], v[48:51]
	v_mfma_f32_16x16x32_bf16 v[44:47], v[194:197], v[226:229], v[44:47]
	v_mfma_f32_16x16x32_bf16 v[40:43], v[202:205], v[226:229], v[40:43]
	v_mfma_f32_16x16x32_bf16 v[36:39], v[194:197], v[242:245], v[36:39]
	v_mfma_f32_16x16x32_bf16 v[32:35], v[202:205], v[242:245], v[32:35]
	s_setprio 0
	s_barrier
	s_setprio 2
	s_add_i32 s28, s57, s36
	v_lshl_add_u64 v[152:153], v[152:153], 0, s[16:17]
	s_mov_b32 m0, s28
	ds_read_b128 v[206:209], v150 offset:49152
	ds_read_b128 v[210:213], v150 offset:50176
	ds_read_b128 v[214:217], v150 offset:51200
	ds_read_b128 v[218:221], v150 offset:52224
	ds_read_b128 v[222:225], v150 offset:53248
	ds_read_b128 v[226:229], v150 offset:54272
	ds_read_b128 v[230:233], v150 offset:55296
	ds_read_b128 v[242:245], v150 offset:56320
	global_load_lds_dwordx4 v[152:153], off
	s_add_i32 m0, s28, 0x2000
	s_add_u32 s26, s26, 0x40080
	v_lshl_add_u64 v[152:153], v[154:155], 0, s[16:17]
	s_addc_u32 s27, s27, 0
	s_add_i32 s28, s58, s36
	global_load_lds_dwordx4 v[152:153], off
	v_lshl_add_u64 v[152:153], s[26:27], 0, v[96:97]
	s_mov_b32 m0, s28
	s_nop 0
	global_load_lds_dwordx4 v[152:153], off
	v_lshl_add_u64 v[152:153], s[26:27], 0, v[130:131]
	s_add_i32 m0, s28, 0x2000
	s_nop 0
	global_load_lds_dwordx4 v[152:153], off
	v_lshl_add_u64 v[152:153], v[156:157], 0, s[16:17]
	s_mov_b32 m0, s45
	s_nop 0
	global_load_lds_dwordx4 v[152:153], off
	v_lshl_add_u64 v[152:153], v[158:159], 0, s[16:17]
	s_mov_b32 m0, s46
	s_nop 0
	global_load_lds_dwordx4 v[152:153], off
	s_setprio 1
	s_waitcnt vmcnt(8) lgkmcnt(0)
	s_barrier
	v_mfma_f32_16x16x32_bf16 v[92:95], v[162:165], v[206:209], v[92:95]
	v_mfma_f32_16x16x32_bf16 v[88:91], v[170:173], v[206:209], v[88:91]
	v_mfma_f32_16x16x32_bf16 v[84:87], v[162:165], v[214:217], v[84:87]
	v_mfma_f32_16x16x32_bf16 v[80:83], v[170:173], v[214:217], v[80:83]
	v_mfma_f32_16x16x32_bf16 v[76:79], v[162:165], v[222:225], v[76:79]
	v_mfma_f32_16x16x32_bf16 v[72:75], v[170:173], v[222:225], v[72:75]
	v_mfma_f32_16x16x32_bf16 v[60:63], v[162:165], v[230:233], v[60:63]
	v_mfma_f32_16x16x32_bf16 v[56:59], v[170:173], v[230:233], v[56:59]
	v_mfma_f32_16x16x32_bf16 v[92:95], v[166:169], v[210:213], v[92:95]
	v_mfma_f32_16x16x32_bf16 v[88:91], v[186:189], v[210:213], v[88:91]
	v_mfma_f32_16x16x32_bf16 v[84:87], v[166:169], v[218:221], v[84:87]
	v_mfma_f32_16x16x32_bf16 v[80:83], v[186:189], v[218:221], v[80:83]
	v_mfma_f32_16x16x32_bf16 v[76:79], v[166:169], v[226:229], v[76:79]
	v_mfma_f32_16x16x32_bf16 v[72:75], v[186:189], v[226:229], v[72:75]
	v_mfma_f32_16x16x32_bf16 v[60:63], v[166:169], v[242:245], v[60:63]
	v_mfma_f32_16x16x32_bf16 v[56:59], v[186:189], v[242:245], v[56:59]
	s_setprio 0
	s_setprio 1
	v_mfma_f32_16x16x32_bf16 v[28:31], v[190:193], v[206:209], v[28:31]
	v_mfma_f32_16x16x32_bf16 v[24:27], v[198:201], v[206:209], v[24:27]
	v_mfma_f32_16x16x32_bf16 v[20:23], v[190:193], v[214:217], v[20:23]
	v_mfma_f32_16x16x32_bf16 v[16:19], v[198:201], v[214:217], v[16:19]
	v_mfma_f32_16x16x32_bf16 v[12:15], v[190:193], v[222:225], v[12:15]
	v_mfma_f32_16x16x32_bf16 v[8:11], v[198:201], v[222:225], v[8:11]
	v_mfma_f32_16x16x32_bf16 v[4:7], v[190:193], v[230:233], v[4:7]
	v_mfma_f32_16x16x32_bf16 v[0:3], v[198:201], v[230:233], v[0:3]
	v_mfma_f32_16x16x32_bf16 v[28:31], v[194:197], v[210:213], v[28:31]
	v_mfma_f32_16x16x32_bf16 v[24:27], v[202:205], v[210:213], v[24:27]
	v_mfma_f32_16x16x32_bf16 v[20:23], v[194:197], v[218:221], v[20:23]
	v_mfma_f32_16x16x32_bf16 v[16:19], v[202:205], v[218:221], v[16:19]
	v_mfma_f32_16x16x32_bf16 v[12:15], v[194:197], v[226:229], v[12:15]
	v_mfma_f32_16x16x32_bf16 v[8:11], v[202:205], v[226:229], v[8:11]
	v_mfma_f32_16x16x32_bf16 v[4:7], v[194:197], v[242:245], v[4:7]
	v_mfma_f32_16x16x32_bf16 v[0:3], v[202:205], v[242:245], v[0:3]
	s_setprio 0
	s_barrier
	s_setprio 2
	s_add_i32 s56, s56, 2
	s_add_u32 s14, s14, 0x100
	s_addc_u32 s15, s15, 0
	s_add_u32 s54, s54, 0x100
	s_addc_u32 s55, s55, 0
	s_cmp_gt_u32 s56, 13
	s_cbranch_scc0 .LBB0_393
	s_and_b64 vcc, exec, s[12:13]
	s_cbranch_vccz .LBB0_396
	s_barrier

.LBB0_427:
	s_add_u32 s14, s4, 0xfffc0080
	s_addc_u32 s15, s5, -1
	s_add_i32 s62, 0, 0x10000
	s_cmp_eq_u32 s61, 12
	s_cselect_b32 s37, s29, s15
	s_cselect_b32 s36, s57, s14
	v_add_u32_e32 v154, s62, v169
	s_cselect_b32 s15, s27, s60
	s_cselect_b32 s14, s58, s59
	s_add_i32 s64, 0, 0x14000
	ds_read_b128 v[142:145], v154
	ds_read_b128 v[146:149], v154 offset:1024
	ds_read_b128 v[150:153], v154 offset:2048
	ds_read_b128 v[162:165], v154 offset:3072
	v_add_u32_e32 v154, s64, v169
	ds_read_b128 v[186:189], v154
	ds_read_b128 v[190:193], v154 offset:1024
	ds_read_b128 v[194:197], v154 offset:2048
	ds_read_b128 v[198:201], v154 offset:3072
	v_lshl_add_u64 v[154:155], s[4:5], 0, v[138:139]
	s_add_i32 m0, s43, 0xc000
	ds_read_b128 v[202:205], v173
	ds_read_b128 v[206:209], v173 offset:1024
	ds_read_b128 v[210:213], v173 offset:2048
	ds_read_b128 v[214:217], v173 offset:3072
	ds_read_b128 v[218:221], v173 offset:4096
	ds_read_b128 v[222:225], v173 offset:5120
	ds_read_b128 v[226:229], v173 offset:6144
	ds_read_b128 v[230:233], v173 offset:7168
	global_load_lds_dwordx4 v[154:155], off
	v_lshl_add_u64 v[154:155], s[4:5], 0, v[140:141]
	s_add_i32 m0, s43, 0xe000
	s_nop 0
	global_load_lds_dwordx4 v[154:155], off
	s_setprio 1
	s_waitcnt vmcnt(8) lgkmcnt(0)
	s_barrier
	v_mfma_f32_16x16x32_bf16 v[126:129], v[142:145], v[202:205], v[126:129]
	v_mfma_f32_16x16x32_bf16 v[122:125], v[150:153], v[202:205], v[122:125]
	v_mfma_f32_16x16x32_bf16 v[110:113], v[142:145], v[210:213], v[110:113]
	v_mfma_f32_16x16x32_bf16 v[106:109], v[150:153], v[210:213], v[106:109]
	v_mfma_f32_16x16x32_bf16 v[92:95], v[142:145], v[218:221], v[92:95]
	v_mfma_f32_16x16x32_bf16 v[88:91], v[150:153], v[218:221], v[88:91]
	v_mfma_f32_16x16x32_bf16 v[76:79], v[142:145], v[226:229], v[76:79]
	v_mfma_f32_16x16x32_bf16 v[72:75], v[150:153], v[226:229], v[72:75]
	v_mfma_f32_16x16x32_bf16 v[126:129], v[146:149], v[206:209], v[126:129]
	v_mfma_f32_16x16x32_bf16 v[122:125], v[162:165], v[206:209], v[122:125]
	v_mfma_f32_16x16x32_bf16 v[110:113], v[146:149], v[214:217], v[110:113]
	v_mfma_f32_16x16x32_bf16 v[106:109], v[162:165], v[214:217], v[106:109]
	v_mfma_f32_16x16x32_bf16 v[92:95], v[146:149], v[222:225], v[92:95]
	v_mfma_f32_16x16x32_bf16 v[88:91], v[162:165], v[222:225], v[88:91]
	v_mfma_f32_16x16x32_bf16 v[76:79], v[146:149], v[230:233], v[76:79]
	v_mfma_f32_16x16x32_bf16 v[72:75], v[162:165], v[230:233], v[72:75]
	s_setprio 0
	s_setprio 1
	v_mfma_f32_16x16x32_bf16 v[118:121], v[186:189], v[202:205], v[118:121]
	v_mfma_f32_16x16x32_bf16 v[114:117], v[194:197], v[202:205], v[114:117]
	v_mfma_f32_16x16x32_bf16 v[102:105], v[186:189], v[210:213], v[102:105]
	v_mfma_f32_16x16x32_bf16 v[98:101], v[194:197], v[210:213], v[98:101]
	v_mfma_f32_16x16x32_bf16 v[84:87], v[186:189], v[218:221], v[84:87]
	v_mfma_f32_16x16x32_bf16 v[80:83], v[194:197], v[218:221], v[80:83]
	v_mfma_f32_16x16x32_bf16 v[68:71], v[186:189], v[226:229], v[68:71]
	v_mfma_f32_16x16x32_bf16 v[64:67], v[194:197], v[226:229], v[64:67]
	v_mfma_f32_16x16x32_bf16 v[118:121], v[190:193], v[206:209], v[118:121]
	v_mfma_f32_16x16x32_bf16 v[114:117], v[198:201], v[206:209], v[114:117]
	v_mfma_f32_16x16x32_bf16 v[102:105], v[190:193], v[214:217], v[102:105]
	v_mfma_f32_16x16x32_bf16 v[98:101], v[198:201], v[214:217], v[98:101]
	v_mfma_f32_16x16x32_bf16 v[84:87], v[190:193], v[222:225], v[84:87]
	v_mfma_f32_16x16x32_bf16 v[80:83], v[198:201], v[222:225], v[80:83]
	v_mfma_f32_16x16x32_bf16 v[68:71], v[190:193], v[230:233], v[68:71]
	v_mfma_f32_16x16x32_bf16 v[64:67], v[198:201], v[230:233], v[64:67]
	s_setprio 0
	s_barrier
	s_setprio 2
	s_add_i32 s62, s62, s42
	v_lshl_add_u64 v[154:155], s[14:15], 0, v[96:97]
	s_mov_b32 m0, s62
	ds_read_b128 v[202:205], v173 offset:16384
	ds_read_b128 v[206:209], v173 offset:17408
	ds_read_b128 v[210:213], v173 offset:18432
	ds_read_b128 v[214:217], v173 offset:19456
	ds_read_b128 v[218:221], v173 offset:20480
	ds_read_b128 v[222:225], v173 offset:21504
	ds_read_b128 v[226:229], v173 offset:22528
	ds_read_b128 v[230:233], v173 offset:23552
	global_load_lds_dwordx4 v[154:155], off
	s_add_i32 m0, s62, 0x2000
	s_add_u32 s62, s14, 0x40000
	v_lshl_add_u64 v[156:157], s[14:15], 0, v[130:131]
	s_addc_u32 s63, s15, 0
	s_add_i32 s64, s64, s42
	global_load_lds_dwordx4 v[156:157], off
	v_lshl_add_u64 v[158:159], s[62:63], 0, v[96:97]
	s_mov_b32 m0, s64
	v_lshl_add_u64 v[166:167], s[36:37], 0, v[132:133]
	global_load_lds_dwordx4 v[158:159], off
	v_lshl_add_u64 v[158:159], s[62:63], 0, v[130:131]
	s_add_i32 m0, s64, 0x2000
	s_nop 0
	global_load_lds_dwordx4 v[158:159], off
	v_lshl_add_u64 v[158:159], s[36:37], 0, v[134:135]
	s_mov_b32 m0, s43
	s_nop 0
	global_load_lds_dwordx4 v[158:159], off
	s_mov_b32 m0, s44
	s_nop 0
	global_load_lds_dwordx4 v[166:167], off
	s_setprio 1
	s_waitcnt vmcnt(8) lgkmcnt(0)
	s_barrier
	v_mfma_f32_16x16x32_bf16 v[60:63], v[142:145], v[202:205], v[60:63]
	v_mfma_f32_16x16x32_bf16 v[56:59], v[150:153], v[202:205], v[56:59]
	v_mfma_f32_16x16x32_bf16 v[44:47], v[142:145], v[210:213], v[44:47]
	v_mfma_f32_16x16x32_bf16 v[40:43], v[150:153], v[210:213], v[40:43]
	v_mfma_f32_16x16x32_bf16 v[28:31], v[142:145], v[218:221], v[28:31]
	v_mfma_f32_16x16x32_bf16 v[24:27], v[150:153], v[218:221], v[24:27]
	v_mfma_f32_16x16x32_bf16 v[12:15], v[142:145], v[226:229], v[12:15]
	v_mfma_f32_16x16x32_bf16 v[8:11], v[150:153], v[226:229], v[8:11]
	v_mfma_f32_16x16x32_bf16 v[60:63], v[146:149], v[206:209], v[60:63]
	v_mfma_f32_16x16x32_bf16 v[56:59], v[162:165], v[206:209], v[56:59]
	v_mfma_f32_16x16x32_bf16 v[44:47], v[146:149], v[214:217], v[44:47]
	v_mfma_f32_16x16x32_bf16 v[40:43], v[162:165], v[214:217], v[40:43]
	v_mfma_f32_16x16x32_bf16 v[28:31], v[146:149], v[222:225], v[28:31]
	v_mfma_f32_16x16x32_bf16 v[24:27], v[162:165], v[222:225], v[24:27]
	v_mfma_f32_16x16x32_bf16 v[12:15], v[146:149], v[230:233], v[12:15]
	v_mfma_f32_16x16x32_bf16 v[8:11], v[162:165], v[230:233], v[8:11]
	s_setprio 0
	s_setprio 1
	v_mfma_f32_16x16x32_bf16 v[52:55], v[186:189], v[202:205], v[52:55]
	v_mfma_f32_16x16x32_bf16 v[48:51], v[194:197], v[202:205], v[48:51]
	v_mfma_f32_16x16x32_bf16 v[36:39], v[186:189], v[210:213], v[36:39]
	v_mfma_f32_16x16x32_bf16 v[32:35], v[194:197], v[210:213], v[32:35]
	v_mfma_f32_16x16x32_bf16 v[20:23], v[186:189], v[218:221], v[20:23]
	v_mfma_f32_16x16x32_bf16 v[16:19], v[194:197], v[218:221], v[16:19]
	v_mfma_f32_16x16x32_bf16 v[4:7], v[186:189], v[226:229], v[4:7]
	v_mfma_f32_16x16x32_bf16 v[0:3], v[194:197], v[226:229], v[0:3]
	v_mfma_f32_16x16x32_bf16 v[52:55], v[190:193], v[206:209], v[52:55]
	v_mfma_f32_16x16x32_bf16 v[48:51], v[198:201], v[206:209], v[48:51]
	v_mfma_f32_16x16x32_bf16 v[36:39], v[190:193], v[214:217], v[36:39]
	v_mfma_f32_16x16x32_bf16 v[32:35], v[198:201], v[214:217], v[32:35]
	v_mfma_f32_16x16x32_bf16 v[20:23], v[190:193], v[222:225], v[20:23]
	v_mfma_f32_16x16x32_bf16 v[16:19], v[198:201], v[222:225], v[16:19]
	v_mfma_f32_16x16x32_bf16 v[4:7], v[190:193], v[230:233], v[4:7]
	v_mfma_f32_16x16x32_bf16 v[0:3], v[198:201], v[230:233], v[0:3]
	s_setprio 0
	s_barrier
	s_setprio 2
	s_add_i32 s62, 0, 0x18000
	s_add_i32 s63, 0, 0x1c000
	v_add_u32_e32 v162, s62, v169
	v_add_u32_e32 v182, s63, v169
	ds_read_b128 v[142:145], v162
	ds_read_b128 v[146:149], v162 offset:1024
	ds_read_b128 v[150:153], v162 offset:2048
	ds_read_b128 v[162:165], v162 offset:3072
	ds_read_b128 v[186:189], v182
	ds_read_b128 v[190:193], v182 offset:1024
	ds_read_b128 v[194:197], v182 offset:2048
	ds_read_b128 v[198:201], v182 offset:3072
	s_add_u32 s36, s36, 0x40000
	s_addc_u32 s37, s37, 0
	s_mov_b32 m0, s45
	v_lshl_add_u64 v[182:183], s[36:37], 0, v[134:135]
	ds_read_b128 v[202:205], v173 offset:32768
	ds_read_b128 v[206:209], v173 offset:33792
	ds_read_b128 v[210:213], v173 offset:34816
	ds_read_b128 v[214:217], v173 offset:35840
	ds_read_b128 v[218:221], v173 offset:36864
	ds_read_b128 v[222:225], v173 offset:37888
	ds_read_b128 v[226:229], v173 offset:38912
	ds_read_b128 v[230:233], v173 offset:39936
	global_load_lds_dwordx4 v[182:183], off
	v_lshl_add_u64 v[182:183], s[36:37], 0, v[132:133]
	s_mov_b32 m0, s46
	s_nop 0
	global_load_lds_dwordx4 v[182:183], off
	s_setprio 1
	s_waitcnt vmcnt(8) lgkmcnt(0)
	s_barrier
	v_mfma_f32_16x16x32_bf16 v[126:129], v[142:145], v[202:205], v[126:129]
	v_mfma_f32_16x16x32_bf16 v[122:125], v[150:153], v[202:205], v[122:125]
	v_mfma_f32_16x16x32_bf16 v[110:113], v[142:145], v[210:213], v[110:113]
	v_mfma_f32_16x16x32_bf16 v[106:109], v[150:153], v[210:213], v[106:109]
	v_mfma_f32_16x16x32_bf16 v[92:95], v[142:145], v[218:221], v[92:95]
	v_mfma_f32_16x16x32_bf16 v[88:91], v[150:153], v[218:221], v[88:91]
	v_mfma_f32_16x16x32_bf16 v[76:79], v[142:145], v[226:229], v[76:79]
	v_mfma_f32_16x16x32_bf16 v[72:75], v[150:153], v[226:229], v[72:75]
	v_mfma_f32_16x16x32_bf16 v[126:129], v[146:149], v[206:209], v[126:129]
	v_mfma_f32_16x16x32_bf16 v[122:125], v[162:165], v[206:209], v[122:125]
	v_mfma_f32_16x16x32_bf16 v[110:113], v[146:149], v[214:217], v[110:113]
	v_mfma_f32_16x16x32_bf16 v[106:109], v[162:165], v[214:217], v[106:109]
	v_mfma_f32_16x16x32_bf16 v[92:95], v[146:149], v[222:225], v[92:95]
	v_mfma_f32_16x16x32_bf16 v[88:91], v[162:165], v[222:225], v[88:91]
	v_mfma_f32_16x16x32_bf16 v[76:79], v[146:149], v[230:233], v[76:79]
	v_mfma_f32_16x16x32_bf16 v[72:75], v[162:165], v[230:233], v[72:75]
	s_setprio 0
	s_setprio 1
	v_mfma_f32_16x16x32_bf16 v[118:121], v[186:189], v[202:205], v[118:121]
	v_mfma_f32_16x16x32_bf16 v[114:117], v[194:197], v[202:205], v[114:117]
	v_mfma_f32_16x16x32_bf16 v[102:105], v[186:189], v[210:213], v[102:105]
	v_mfma_f32_16x16x32_bf16 v[98:101], v[194:197], v[210:213], v[98:101]
	v_mfma_f32_16x16x32_bf16 v[84:87], v[186:189], v[218:221], v[84:87]
	v_mfma_f32_16x16x32_bf16 v[80:83], v[194:197], v[218:221], v[80:83]
	v_mfma_f32_16x16x32_bf16 v[68:71], v[186:189], v[226:229], v[68:71]
	v_mfma_f32_16x16x32_bf16 v[64:67], v[194:197], v[226:229], v[64:67]
	v_mfma_f32_16x16x32_bf16 v[118:121], v[190:193], v[206:209], v[118:121]
	v_mfma_f32_16x16x32_bf16 v[114:117], v[198:201], v[206:209], v[114:117]
	v_mfma_f32_16x16x32_bf16 v[102:105], v[190:193], v[214:217], v[102:105]
	v_mfma_f32_16x16x32_bf16 v[98:101], v[198:201], v[214:217], v[98:101]
	v_mfma_f32_16x16x32_bf16 v[84:87], v[190:193], v[222:225], v[84:87]
	v_mfma_f32_16x16x32_bf16 v[80:83], v[198:201], v[222:225], v[80:83]
	v_mfma_f32_16x16x32_bf16 v[68:71], v[190:193], v[230:233], v[68:71]
	v_mfma_f32_16x16x32_bf16 v[64:67], v[198:201], v[230:233], v[64:67]
	s_setprio 0
	s_barrier
	s_setprio 2
	s_add_i32 s36, s62, s42
	v_lshl_add_u64 v[154:155], v[154:155], 0, s[16:17]
	s_mov_b32 m0, s36
	ds_read_b128 v[202:205], v173 offset:49152
	ds_read_b128 v[206:209], v173 offset:50176
	ds_read_b128 v[210:213], v173 offset:51200
	ds_read_b128 v[214:217], v173 offset:52224
	ds_read_b128 v[218:221], v173 offset:53248
	ds_read_b128 v[222:225], v173 offset:54272
	ds_read_b128 v[226:229], v173 offset:55296
	ds_read_b128 v[230:233], v173 offset:56320
	global_load_lds_dwordx4 v[154:155], off
	s_add_i32 m0, s36, 0x2000
	s_add_u32 s14, s14, 0x40080
	v_lshl_add_u64 v[154:155], v[156:157], 0, s[16:17]
	s_addc_u32 s15, s15, 0
	s_add_i32 s36, s63, s42
	global_load_lds_dwordx4 v[154:155], off
	v_lshl_add_u64 v[154:155], s[14:15], 0, v[96:97]
	s_mov_b32 m0, s36
	s_nop 0
	global_load_lds_dwordx4 v[154:155], off
	v_lshl_add_u64 v[154:155], s[14:15], 0, v[130:131]
	s_add_i32 m0, s36, 0x2000
	s_nop 0
	global_load_lds_dwordx4 v[154:155], off
	v_lshl_add_u64 v[154:155], v[158:159], 0, s[16:17]
	s_mov_b32 m0, s52
	s_nop 0
	global_load_lds_dwordx4 v[154:155], off
	v_lshl_add_u64 v[154:155], v[166:167], 0, s[16:17]
	s_mov_b32 m0, s53
	s_nop 0
	global_load_lds_dwordx4 v[154:155], off
	s_setprio 1
	s_waitcnt vmcnt(8) lgkmcnt(0)
	s_barrier
	v_mfma_f32_16x16x32_bf16 v[60:63], v[142:145], v[202:205], v[60:63]
	v_mfma_f32_16x16x32_bf16 v[56:59], v[150:153], v[202:205], v[56:59]
	v_mfma_f32_16x16x32_bf16 v[44:47], v[142:145], v[210:213], v[44:47]
	v_mfma_f32_16x16x32_bf16 v[40:43], v[150:153], v[210:213], v[40:43]
	v_mfma_f32_16x16x32_bf16 v[28:31], v[142:145], v[218:221], v[28:31]
	v_mfma_f32_16x16x32_bf16 v[24:27], v[150:153], v[218:221], v[24:27]
	v_mfma_f32_16x16x32_bf16 v[12:15], v[142:145], v[226:229], v[12:15]
	v_mfma_f32_16x16x32_bf16 v[8:11], v[150:153], v[226:229], v[8:11]
	v_mfma_f32_16x16x32_bf16 v[60:63], v[146:149], v[206:209], v[60:63]
	v_mfma_f32_16x16x32_bf16 v[56:59], v[162:165], v[206:209], v[56:59]
	v_mfma_f32_16x16x32_bf16 v[44:47], v[146:149], v[214:217], v[44:47]
	v_mfma_f32_16x16x32_bf16 v[40:43], v[162:165], v[214:217], v[40:43]
	v_mfma_f32_16x16x32_bf16 v[28:31], v[146:149], v[222:225], v[28:31]
	v_mfma_f32_16x16x32_bf16 v[24:27], v[162:165], v[222:225], v[24:27]
	v_mfma_f32_16x16x32_bf16 v[12:15], v[146:149], v[230:233], v[12:15]
	v_mfma_f32_16x16x32_bf16 v[8:11], v[162:165], v[230:233], v[8:11]
	s_setprio 0
	s_setprio 1
	v_mfma_f32_16x16x32_bf16 v[52:55], v[186:189], v[202:205], v[52:55]
	v_mfma_f32_16x16x32_bf16 v[48:51], v[194:197], v[202:205], v[48:51]
	v_mfma_f32_16x16x32_bf16 v[36:39], v[186:189], v[210:213], v[36:39]
	v_mfma_f32_16x16x32_bf16 v[32:35], v[194:197], v[210:213], v[32:35]
	v_mfma_f32_16x16x32_bf16 v[20:23], v[186:189], v[218:221], v[20:23]
	v_mfma_f32_16x16x32_bf16 v[16:19], v[194:197], v[218:221], v[16:19]
	v_mfma_f32_16x16x32_bf16 v[4:7], v[186:189], v[226:229], v[4:7]
	v_mfma_f32_16x16x32_bf16 v[0:3], v[194:197], v[226:229], v[0:3]
	v_mfma_f32_16x16x32_bf16 v[52:55], v[190:193], v[206:209], v[52:55]
	v_mfma_f32_16x16x32_bf16 v[48:51], v[198:201], v[206:209], v[48:51]
	v_mfma_f32_16x16x32_bf16 v[36:39], v[190:193], v[214:217], v[36:39]
	v_mfma_f32_16x16x32_bf16 v[32:35], v[198:201], v[214:217], v[32:35]
	v_mfma_f32_16x16x32_bf16 v[20:23], v[190:193], v[222:225], v[20:23]
	v_mfma_f32_16x16x32_bf16 v[16:19], v[198:201], v[222:225], v[16:19]
	v_mfma_f32_16x16x32_bf16 v[4:7], v[190:193], v[230:233], v[4:7]
	v_mfma_f32_16x16x32_bf16 v[0:3], v[198:201], v[230:233], v[0:3]
	s_setprio 0
	s_barrier
	s_setprio 2
	s_add_i32 s61, s61, 2
	s_add_u32 s4, s4, 0x100
	s_addc_u32 s5, s5, 0
	s_add_u32 s59, s59, 0x100
	s_addc_u32 s60, s60, 0
	s_cmp_gt_u32 s61, 13
	s_cbranch_scc0 .LBB0_427
	s_and_b64 vcc, exec, s[24:25]
	s_cbranch_vccz .LBB0_430
	s_barrier

.LBB0_449:
	s_add_u32 s30, s14, 0xfffc0080
	s_addc_u32 s31, s15, -1
	s_add_i32 s60, 0, 0x10000
	s_cmp_eq_u32 s59, 12
	s_cselect_b32 s35, s25, s31
	s_cselect_b32 s34, s55, s30
	v_add_u32_e32 v96, s60, v151
	s_cselect_b32 s31, s13, s58
	s_cselect_b32 s30, s56, s57
	s_add_i32 s62, 0, 0x14000
	ds_read_b128 v[144:147], v96
	ds_read_b128 v[164:167], v96 offset:1024
	ds_read_b128 v[168:171], v96 offset:2048
	ds_read_b128 v[186:189], v96 offset:3072
	v_add_u32_e32 v96, s62, v151
	ds_read_b128 v[190:193], v96
	ds_read_b128 v[194:197], v96 offset:1024
	ds_read_b128 v[198:201], v96 offset:2048
	ds_read_b128 v[202:205], v96 offset:3072
	v_lshl_add_u64 v[148:149], s[14:15], 0, v[140:141]
	s_add_i32 m0, s41, 0xc000
	ds_read_b128 v[206:209], v163
	ds_read_b128 v[210:213], v163 offset:1024
	ds_read_b128 v[214:217], v163 offset:2048
	ds_read_b128 v[218:221], v163 offset:3072
	ds_read_b128 v[222:225], v163 offset:4096
	ds_read_b128 v[226:229], v163 offset:5120
	ds_read_b128 v[230:233], v163 offset:6144
	ds_read_b128 v[242:245], v163 offset:7168
	global_load_lds_dwordx4 v[148:149], off
	v_lshl_add_u64 v[148:149], s[14:15], 0, v[142:143]
	s_add_i32 m0, s41, 0xe000
	s_nop 0
	global_load_lds_dwordx4 v[148:149], off
	s_setprio 1
	s_waitcnt vmcnt(8) lgkmcnt(0)
	s_barrier
	v_mfma_f32_16x16x32_bf16 v[126:129], v[144:147], v[206:209], v[126:129]
	v_mfma_f32_16x16x32_bf16 v[122:125], v[168:171], v[206:209], v[122:125]
	v_mfma_f32_16x16x32_bf16 v[110:113], v[144:147], v[214:217], v[110:113]
	v_mfma_f32_16x16x32_bf16 v[106:109], v[168:171], v[214:217], v[106:109]
	v_mfma_f32_16x16x32_bf16 v[92:95], v[144:147], v[222:225], v[92:95]
	v_mfma_f32_16x16x32_bf16 v[88:91], v[168:171], v[222:225], v[88:91]
	v_mfma_f32_16x16x32_bf16 v[76:79], v[144:147], v[230:233], v[76:79]
	v_mfma_f32_16x16x32_bf16 v[72:75], v[168:171], v[230:233], v[72:75]
	v_mfma_f32_16x16x32_bf16 v[126:129], v[164:167], v[210:213], v[126:129]
	v_mfma_f32_16x16x32_bf16 v[122:125], v[186:189], v[210:213], v[122:125]
	v_mfma_f32_16x16x32_bf16 v[110:113], v[164:167], v[218:221], v[110:113]
	v_mfma_f32_16x16x32_bf16 v[106:109], v[186:189], v[218:221], v[106:109]
	v_mfma_f32_16x16x32_bf16 v[92:95], v[164:167], v[226:229], v[92:95]
	v_mfma_f32_16x16x32_bf16 v[88:91], v[186:189], v[226:229], v[88:91]
	v_mfma_f32_16x16x32_bf16 v[76:79], v[164:167], v[242:245], v[76:79]
	v_mfma_f32_16x16x32_bf16 v[72:75], v[186:189], v[242:245], v[72:75]
	s_setprio 0
	s_setprio 1
	v_mfma_f32_16x16x32_bf16 v[118:121], v[190:193], v[206:209], v[118:121]
	v_mfma_f32_16x16x32_bf16 v[114:117], v[198:201], v[206:209], v[114:117]
	v_mfma_f32_16x16x32_bf16 v[102:105], v[190:193], v[214:217], v[102:105]
	v_mfma_f32_16x16x32_bf16 v[98:101], v[198:201], v[214:217], v[98:101]
	v_mfma_f32_16x16x32_bf16 v[84:87], v[190:193], v[222:225], v[84:87]
	v_mfma_f32_16x16x32_bf16 v[80:83], v[198:201], v[222:225], v[80:83]
	v_mfma_f32_16x16x32_bf16 v[68:71], v[190:193], v[230:233], v[68:71]
	v_mfma_f32_16x16x32_bf16 v[64:67], v[198:201], v[230:233], v[64:67]
	v_mfma_f32_16x16x32_bf16 v[118:121], v[194:197], v[210:213], v[118:121]
	v_mfma_f32_16x16x32_bf16 v[114:117], v[202:205], v[210:213], v[114:117]
	v_mfma_f32_16x16x32_bf16 v[102:105], v[194:197], v[218:221], v[102:105]
	v_mfma_f32_16x16x32_bf16 v[98:101], v[202:205], v[218:221], v[98:101]
	v_mfma_f32_16x16x32_bf16 v[84:87], v[194:197], v[226:229], v[84:87]
	v_mfma_f32_16x16x32_bf16 v[80:83], v[202:205], v[226:229], v[80:83]
	v_mfma_f32_16x16x32_bf16 v[68:71], v[194:197], v[242:245], v[68:71]
	v_mfma_f32_16x16x32_bf16 v[64:67], v[202:205], v[242:245], v[64:67]
	s_setprio 0
	s_barrier
	s_setprio 2
	s_add_i32 s60, s60, s40
	v_lshl_add_u64 v[148:149], s[30:31], 0, v[134:135]
	s_mov_b32 m0, s60
	ds_read_b128 v[206:209], v163 offset:16384
	ds_read_b128 v[210:213], v163 offset:17408
	ds_read_b128 v[214:217], v163 offset:18432
	ds_read_b128 v[218:221], v163 offset:19456
	ds_read_b128 v[222:225], v163 offset:20480
	ds_read_b128 v[226:229], v163 offset:21504
	ds_read_b128 v[230:233], v163 offset:22528
	ds_read_b128 v[242:245], v163 offset:23552
	global_load_lds_dwordx4 v[148:149], off
	s_add_i32 m0, s60, 0x2000
	s_add_u32 s60, s30, 0x40000
	v_lshl_add_u64 v[154:155], s[30:31], 0, v[130:131]
	s_addc_u32 s61, s31, 0
	s_add_i32 s62, s62, s40
	global_load_lds_dwordx4 v[154:155], off
	v_lshl_add_u64 v[156:157], s[60:61], 0, v[134:135]
	s_mov_b32 m0, s62
	v_lshl_add_u64 v[158:159], s[34:35], 0, v[132:133]
	global_load_lds_dwordx4 v[156:157], off
	v_lshl_add_u64 v[156:157], s[60:61], 0, v[130:131]
	s_add_i32 m0, s62, 0x2000
	s_nop 0
	global_load_lds_dwordx4 v[156:157], off
	v_lshl_add_u64 v[156:157], s[34:35], 0, v[136:137]
	s_mov_b32 m0, s41
	s_nop 0
	global_load_lds_dwordx4 v[156:157], off
	s_mov_b32 m0, s42
	s_nop 0
	global_load_lds_dwordx4 v[158:159], off
	s_setprio 1
	s_waitcnt vmcnt(8) lgkmcnt(0)
	s_barrier
	v_mfma_f32_16x16x32_bf16 v[60:63], v[144:147], v[206:209], v[60:63]
	v_mfma_f32_16x16x32_bf16 v[56:59], v[168:171], v[206:209], v[56:59]
	v_mfma_f32_16x16x32_bf16 v[44:47], v[144:147], v[214:217], v[44:47]
	v_mfma_f32_16x16x32_bf16 v[40:43], v[168:171], v[214:217], v[40:43]
	v_mfma_f32_16x16x32_bf16 v[28:31], v[144:147], v[222:225], v[28:31]
	v_mfma_f32_16x16x32_bf16 v[24:27], v[168:171], v[222:225], v[24:27]
	v_mfma_f32_16x16x32_bf16 v[12:15], v[144:147], v[230:233], v[12:15]
	v_mfma_f32_16x16x32_bf16 v[8:11], v[168:171], v[230:233], v[8:11]
	v_mfma_f32_16x16x32_bf16 v[60:63], v[164:167], v[210:213], v[60:63]
	v_mfma_f32_16x16x32_bf16 v[56:59], v[186:189], v[210:213], v[56:59]
	v_mfma_f32_16x16x32_bf16 v[44:47], v[164:167], v[218:221], v[44:47]
	v_mfma_f32_16x16x32_bf16 v[40:43], v[186:189], v[218:221], v[40:43]
	v_mfma_f32_16x16x32_bf16 v[28:31], v[164:167], v[226:229], v[28:31]
	v_mfma_f32_16x16x32_bf16 v[24:27], v[186:189], v[226:229], v[24:27]
	v_mfma_f32_16x16x32_bf16 v[12:15], v[164:167], v[242:245], v[12:15]
	v_mfma_f32_16x16x32_bf16 v[8:11], v[186:189], v[242:245], v[8:11]
	s_setprio 0
	s_setprio 1
	v_mfma_f32_16x16x32_bf16 v[52:55], v[190:193], v[206:209], v[52:55]
	v_mfma_f32_16x16x32_bf16 v[48:51], v[198:201], v[206:209], v[48:51]
	v_mfma_f32_16x16x32_bf16 v[36:39], v[190:193], v[214:217], v[36:39]
	v_mfma_f32_16x16x32_bf16 v[32:35], v[198:201], v[214:217], v[32:35]
	v_mfma_f32_16x16x32_bf16 v[20:23], v[190:193], v[222:225], v[20:23]
	v_mfma_f32_16x16x32_bf16 v[16:19], v[198:201], v[222:225], v[16:19]
	v_mfma_f32_16x16x32_bf16 v[4:7], v[190:193], v[230:233], v[4:7]
	v_mfma_f32_16x16x32_bf16 v[0:3], v[198:201], v[230:233], v[0:3]
	v_mfma_f32_16x16x32_bf16 v[52:55], v[194:197], v[210:213], v[52:55]
	v_mfma_f32_16x16x32_bf16 v[48:51], v[202:205], v[210:213], v[48:51]
	v_mfma_f32_16x16x32_bf16 v[36:39], v[194:197], v[218:221], v[36:39]
	v_mfma_f32_16x16x32_bf16 v[32:35], v[202:205], v[218:221], v[32:35]
	v_mfma_f32_16x16x32_bf16 v[20:23], v[194:197], v[226:229], v[20:23]
	v_mfma_f32_16x16x32_bf16 v[16:19], v[202:205], v[226:229], v[16:19]
	v_mfma_f32_16x16x32_bf16 v[4:7], v[194:197], v[242:245], v[4:7]
	v_mfma_f32_16x16x32_bf16 v[0:3], v[202:205], v[242:245], v[0:3]
	s_setprio 0
	s_barrier
	s_setprio 2
	s_add_i32 s60, 0, 0x18000
	v_add_u32_e32 v96, s60, v151
	s_add_i32 s61, 0, 0x1c000
	ds_read_b128 v[144:147], v96
	ds_read_b128 v[164:167], v96 offset:1024
	ds_read_b128 v[168:171], v96 offset:2048
	ds_read_b128 v[186:189], v96 offset:3072
	v_add_u32_e32 v96, s61, v151
	ds_read_b128 v[190:193], v96
	ds_read_b128 v[194:197], v96 offset:1024
	ds_read_b128 v[198:201], v96 offset:2048
	ds_read_b128 v[202:205], v96 offset:3072
	s_add_u32 s34, s34, 0x40000
	s_addc_u32 s35, s35, 0
	s_mov_b32 m0, s43
	v_lshl_add_u64 v[172:173], s[34:35], 0, v[136:137]
	ds_read_b128 v[206:209], v163 offset:32768
	ds_read_b128 v[210:213], v163 offset:33792
	ds_read_b128 v[214:217], v163 offset:34816
	ds_read_b128 v[218:221], v163 offset:35840
	ds_read_b128 v[222:225], v163 offset:36864
	ds_read_b128 v[226:229], v163 offset:37888
	ds_read_b128 v[230:233], v163 offset:38912
	ds_read_b128 v[242:245], v163 offset:39936
	global_load_lds_dwordx4 v[172:173], off
	v_lshl_add_u64 v[172:173], s[34:35], 0, v[132:133]
	s_mov_b32 m0, s44
	s_nop 0
	global_load_lds_dwordx4 v[172:173], off
	s_setprio 1
	s_waitcnt vmcnt(8) lgkmcnt(0)
	s_barrier
	v_mfma_f32_16x16x32_bf16 v[126:129], v[144:147], v[206:209], v[126:129]
	v_mfma_f32_16x16x32_bf16 v[122:125], v[168:171], v[206:209], v[122:125]
	v_mfma_f32_16x16x32_bf16 v[110:113], v[144:147], v[214:217], v[110:113]
	v_mfma_f32_16x16x32_bf16 v[106:109], v[168:171], v[214:217], v[106:109]
	v_mfma_f32_16x16x32_bf16 v[92:95], v[144:147], v[222:225], v[92:95]
	v_mfma_f32_16x16x32_bf16 v[88:91], v[168:171], v[222:225], v[88:91]
	v_mfma_f32_16x16x32_bf16 v[76:79], v[144:147], v[230:233], v[76:79]
	v_mfma_f32_16x16x32_bf16 v[72:75], v[168:171], v[230:233], v[72:75]
	v_mfma_f32_16x16x32_bf16 v[126:129], v[164:167], v[210:213], v[126:129]
	v_mfma_f32_16x16x32_bf16 v[122:125], v[186:189], v[210:213], v[122:125]
	v_mfma_f32_16x16x32_bf16 v[110:113], v[164:167], v[218:221], v[110:113]
	v_mfma_f32_16x16x32_bf16 v[106:109], v[186:189], v[218:221], v[106:109]
	v_mfma_f32_16x16x32_bf16 v[92:95], v[164:167], v[226:229], v[92:95]
	v_mfma_f32_16x16x32_bf16 v[88:91], v[186:189], v[226:229], v[88:91]
	v_mfma_f32_16x16x32_bf16 v[76:79], v[164:167], v[242:245], v[76:79]
	v_mfma_f32_16x16x32_bf16 v[72:75], v[186:189], v[242:245], v[72:75]
	s_setprio 0
	s_setprio 1
	v_mfma_f32_16x16x32_bf16 v[118:121], v[190:193], v[206:209], v[118:121]
	v_mfma_f32_16x16x32_bf16 v[114:117], v[198:201], v[206:209], v[114:117]
	v_mfma_f32_16x16x32_bf16 v[102:105], v[190:193], v[214:217], v[102:105]
	v_mfma_f32_16x16x32_bf16 v[98:101], v[198:201], v[214:217], v[98:101]
	v_mfma_f32_16x16x32_bf16 v[84:87], v[190:193], v[222:225], v[84:87]
	v_mfma_f32_16x16x32_bf16 v[80:83], v[198:201], v[222:225], v[80:83]
	v_mfma_f32_16x16x32_bf16 v[68:71], v[190:193], v[230:233], v[68:71]
	v_mfma_f32_16x16x32_bf16 v[64:67], v[198:201], v[230:233], v[64:67]
	v_mfma_f32_16x16x32_bf16 v[118:121], v[194:197], v[210:213], v[118:121]
	v_mfma_f32_16x16x32_bf16 v[114:117], v[202:205], v[210:213], v[114:117]
	v_mfma_f32_16x16x32_bf16 v[102:105], v[194:197], v[218:221], v[102:105]
	v_mfma_f32_16x16x32_bf16 v[98:101], v[202:205], v[218:221], v[98:101]
	v_mfma_f32_16x16x32_bf16 v[84:87], v[194:197], v[226:229], v[84:87]
	v_mfma_f32_16x16x32_bf16 v[80:83], v[202:205], v[226:229], v[80:83]
	v_mfma_f32_16x16x32_bf16 v[68:71], v[194:197], v[242:245], v[68:71]
	v_mfma_f32_16x16x32_bf16 v[64:67], v[202:205], v[242:245], v[64:67]
	s_setprio 0
	s_barrier
	s_setprio 2
	s_add_i32 s34, s60, s40
	v_lshl_add_u64 v[148:149], v[148:149], 0, s[16:17]
	s_mov_b32 m0, s34
	ds_read_b128 v[206:209], v163 offset:49152
	ds_read_b128 v[210:213], v163 offset:50176
	ds_read_b128 v[214:217], v163 offset:51200
	ds_read_b128 v[218:221], v163 offset:52224
	ds_read_b128 v[222:225], v163 offset:53248
	ds_read_b128 v[226:229], v163 offset:54272
	ds_read_b128 v[230:233], v163 offset:55296
	ds_read_b128 v[242:245], v163 offset:56320
	global_load_lds_dwordx4 v[148:149], off
	s_add_i32 m0, s34, 0x2000
	s_add_u32 s30, s30, 0x40080
	v_lshl_add_u64 v[148:149], v[154:155], 0, s[16:17]
	s_addc_u32 s31, s31, 0
	s_add_i32 s34, s61, s40
	global_load_lds_dwordx4 v[148:149], off
	v_lshl_add_u64 v[148:149], s[30:31], 0, v[134:135]
	s_mov_b32 m0, s34
	s_nop 0
	global_load_lds_dwordx4 v[148:149], off
	v_lshl_add_u64 v[148:149], s[30:31], 0, v[130:131]
	s_add_i32 m0, s34, 0x2000
	s_nop 0
	global_load_lds_dwordx4 v[148:149], off
	v_lshl_add_u64 v[148:149], v[156:157], 0, s[16:17]
	s_mov_b32 m0, s49
	s_nop 0
	global_load_lds_dwordx4 v[148:149], off
	v_lshl_add_u64 v[148:149], v[158:159], 0, s[16:17]
	s_mov_b32 m0, s50
	s_nop 0
	global_load_lds_dwordx4 v[148:149], off
	s_setprio 1
	s_waitcnt vmcnt(8) lgkmcnt(0)
	s_barrier
	v_mfma_f32_16x16x32_bf16 v[60:63], v[144:147], v[206:209], v[60:63]
	v_mfma_f32_16x16x32_bf16 v[56:59], v[168:171], v[206:209], v[56:59]
	v_mfma_f32_16x16x32_bf16 v[44:47], v[144:147], v[214:217], v[44:47]
	v_mfma_f32_16x16x32_bf16 v[40:43], v[168:171], v[214:217], v[40:43]
	v_mfma_f32_16x16x32_bf16 v[28:31], v[144:147], v[222:225], v[28:31]
	v_mfma_f32_16x16x32_bf16 v[24:27], v[168:171], v[222:225], v[24:27]
	v_mfma_f32_16x16x32_bf16 v[12:15], v[144:147], v[230:233], v[12:15]
	v_mfma_f32_16x16x32_bf16 v[8:11], v[168:171], v[230:233], v[8:11]
	v_mfma_f32_16x16x32_bf16 v[60:63], v[164:167], v[210:213], v[60:63]
	v_mfma_f32_16x16x32_bf16 v[56:59], v[186:189], v[210:213], v[56:59]
	v_mfma_f32_16x16x32_bf16 v[44:47], v[164:167], v[218:221], v[44:47]
	v_mfma_f32_16x16x32_bf16 v[40:43], v[186:189], v[218:221], v[40:43]
	v_mfma_f32_16x16x32_bf16 v[28:31], v[164:167], v[226:229], v[28:31]
	v_mfma_f32_16x16x32_bf16 v[24:27], v[186:189], v[226:229], v[24:27]
	v_mfma_f32_16x16x32_bf16 v[12:15], v[164:167], v[242:245], v[12:15]
	v_mfma_f32_16x16x32_bf16 v[8:11], v[186:189], v[242:245], v[8:11]
	s_setprio 0
	s_setprio 1
	v_mfma_f32_16x16x32_bf16 v[52:55], v[190:193], v[206:209], v[52:55]
	v_mfma_f32_16x16x32_bf16 v[48:51], v[198:201], v[206:209], v[48:51]
	v_mfma_f32_16x16x32_bf16 v[36:39], v[190:193], v[214:217], v[36:39]
	v_mfma_f32_16x16x32_bf16 v[32:35], v[198:201], v[214:217], v[32:35]
	v_mfma_f32_16x16x32_bf16 v[20:23], v[190:193], v[222:225], v[20:23]
	v_mfma_f32_16x16x32_bf16 v[16:19], v[198:201], v[222:225], v[16:19]
	v_mfma_f32_16x16x32_bf16 v[4:7], v[190:193], v[230:233], v[4:7]
	v_mfma_f32_16x16x32_bf16 v[0:3], v[198:201], v[230:233], v[0:3]
	v_mfma_f32_16x16x32_bf16 v[52:55], v[194:197], v[210:213], v[52:55]
	v_mfma_f32_16x16x32_bf16 v[48:51], v[202:205], v[210:213], v[48:51]
	v_mfma_f32_16x16x32_bf16 v[36:39], v[194:197], v[218:221], v[36:39]
	v_mfma_f32_16x16x32_bf16 v[32:35], v[202:205], v[218:221], v[32:35]
	v_mfma_f32_16x16x32_bf16 v[20:23], v[194:197], v[226:229], v[20:23]
	v_mfma_f32_16x16x32_bf16 v[16:19], v[202:205], v[226:229], v[16:19]
	v_mfma_f32_16x16x32_bf16 v[4:7], v[194:197], v[242:245], v[4:7]
	v_mfma_f32_16x16x32_bf16 v[0:3], v[202:205], v[242:245], v[0:3]
	s_setprio 0
	s_barrier
	s_setprio 2
	s_add_i32 s59, s59, 2
	s_add_u32 s14, s14, 0x100
	s_addc_u32 s15, s15, 0
	s_add_u32 s57, s57, 0x100
	s_addc_u32 s58, s58, 0
	s_cmp_gt_u32 s59, 13
	s_cbranch_scc0 .LBB0_449
	s_and_b64 vcc, exec, s[18:19]
	s_cbranch_vccz .LBB0_454
	s_barrier
	v_lshl_add_u32 v146, s54, 8, v150
	s_cmp_gt_i32 s53, 7
	s_mov_b64 s[14:15], -1
	s_cbranch_scc1 .LBB0_455

.LBB0_490:
	s_add_i32 s66, s6, 2
	s_add_u32 s67, s4, 0x80
	s_addc_u32 s7, s5, 0
	s_add_i32 s70, 0, 0x10000
	s_cmp_eq_u32 s60, s6
	s_cselect_b32 s7, s43, s7
	s_cselect_b32 s6, s42, s67
	v_add_u32_e32 v148, s70, v151
	s_cselect_b32 s69, s45, s15
	s_cselect_b32 s68, s44, s14
	s_add_i32 s67, 0, 0x14000
	ds_read_b128 v[140:143], v148
	ds_read_b128 v[144:147], v148 offset:1024
	ds_read_b128 v[162:165], v148 offset:2048
	ds_read_b128 v[166:169], v148 offset:3072
	v_add_u32_e32 v148, s67, v151
	ds_read_b128 v[170:173], v148
	ds_read_b128 v[186:189], v148 offset:1024
	ds_read_b128 v[190:193], v148 offset:2048
	ds_read_b128 v[194:197], v148 offset:3072
	v_lshl_add_u64 v[148:149], s[4:5], 0, v[136:137]
	s_add_i32 m0, s52, 0xc000
	ds_read_b128 v[198:201], v153
	ds_read_b128 v[202:205], v153 offset:1024
	ds_read_b128 v[206:209], v153 offset:2048
	ds_read_b128 v[210:213], v153 offset:3072
	ds_read_b128 v[214:217], v153 offset:4096
	ds_read_b128 v[218:221], v153 offset:5120
	ds_read_b128 v[222:225], v153 offset:6144
	ds_read_b128 v[226:229], v153 offset:7168
	global_load_lds_dwordx4 v[148:149], off
	v_lshl_add_u64 v[148:149], s[4:5], 0, v[138:139]
	s_add_i32 m0, s52, 0xe000
	s_nop 0
	global_load_lds_dwordx4 v[148:149], off
	s_setprio 1
	s_waitcnt vmcnt(8) lgkmcnt(0)
	s_barrier
	v_mfma_f32_16x16x32_bf16 v[126:129], v[140:143], v[198:201], v[126:129]
	v_mfma_f32_16x16x32_bf16 v[122:125], v[162:165], v[198:201], v[122:125]
	v_mfma_f32_16x16x32_bf16 v[110:113], v[140:143], v[206:209], v[110:113]
	v_mfma_f32_16x16x32_bf16 v[106:109], v[162:165], v[206:209], v[106:109]
	v_mfma_f32_16x16x32_bf16 v[92:95], v[140:143], v[214:217], v[92:95]
	v_mfma_f32_16x16x32_bf16 v[88:91], v[162:165], v[214:217], v[88:91]
	v_mfma_f32_16x16x32_bf16 v[76:79], v[140:143], v[222:225], v[76:79]
	v_mfma_f32_16x16x32_bf16 v[72:75], v[162:165], v[222:225], v[72:75]
	v_mfma_f32_16x16x32_bf16 v[126:129], v[144:147], v[202:205], v[126:129]
	v_mfma_f32_16x16x32_bf16 v[122:125], v[166:169], v[202:205], v[122:125]
	v_mfma_f32_16x16x32_bf16 v[110:113], v[144:147], v[210:213], v[110:113]
	v_mfma_f32_16x16x32_bf16 v[106:109], v[166:169], v[210:213], v[106:109]
	v_mfma_f32_16x16x32_bf16 v[92:95], v[144:147], v[218:221], v[92:95]
	v_mfma_f32_16x16x32_bf16 v[88:91], v[166:169], v[218:221], v[88:91]
	v_mfma_f32_16x16x32_bf16 v[76:79], v[144:147], v[226:229], v[76:79]
	v_mfma_f32_16x16x32_bf16 v[72:75], v[166:169], v[226:229], v[72:75]
	s_setprio 0
	s_setprio 1
	v_mfma_f32_16x16x32_bf16 v[118:121], v[170:173], v[198:201], v[118:121]
	v_mfma_f32_16x16x32_bf16 v[114:117], v[190:193], v[198:201], v[114:117]
	v_mfma_f32_16x16x32_bf16 v[102:105], v[170:173], v[206:209], v[102:105]
	v_mfma_f32_16x16x32_bf16 v[98:101], v[190:193], v[206:209], v[98:101]
	v_mfma_f32_16x16x32_bf16 v[84:87], v[170:173], v[214:217], v[84:87]
	v_mfma_f32_16x16x32_bf16 v[80:83], v[190:193], v[214:217], v[80:83]
	v_mfma_f32_16x16x32_bf16 v[68:71], v[170:173], v[222:225], v[68:71]
	v_mfma_f32_16x16x32_bf16 v[64:67], v[190:193], v[222:225], v[64:67]
	v_mfma_f32_16x16x32_bf16 v[118:121], v[186:189], v[202:205], v[118:121]
	v_mfma_f32_16x16x32_bf16 v[114:117], v[194:197], v[202:205], v[114:117]
	v_mfma_f32_16x16x32_bf16 v[102:105], v[186:189], v[210:213], v[102:105]
	v_mfma_f32_16x16x32_bf16 v[98:101], v[194:197], v[210:213], v[98:101]
	v_mfma_f32_16x16x32_bf16 v[84:87], v[186:189], v[218:221], v[84:87]
	v_mfma_f32_16x16x32_bf16 v[80:83], v[194:197], v[218:221], v[80:83]
	v_mfma_f32_16x16x32_bf16 v[68:71], v[186:189], v[226:229], v[68:71]
	v_mfma_f32_16x16x32_bf16 v[64:67], v[194:197], v[226:229], v[64:67]
	s_setprio 0
	s_barrier
	s_setprio 2
	s_add_i32 s70, s70, s51
	v_lshl_add_u64 v[148:149], s[68:69], 0, v[96:97]
	s_mov_b32 m0, s70
	ds_read_b128 v[198:201], v153 offset:16384
	ds_read_b128 v[202:205], v153 offset:17408
	ds_read_b128 v[206:209], v153 offset:18432
	ds_read_b128 v[210:213], v153 offset:19456
	ds_read_b128 v[214:217], v153 offset:20480
	ds_read_b128 v[218:221], v153 offset:21504
	ds_read_b128 v[222:225], v153 offset:22528
	ds_read_b128 v[226:229], v153 offset:23552
	global_load_lds_dwordx4 v[148:149], off
	s_add_i32 m0, s70, 0x2000
	v_lshl_add_u64 v[154:155], s[68:69], 0, v[130:131]
	s_add_u32 s68, s68, s46
	s_addc_u32 s69, s69, 0
	s_add_i32 s67, s67, s51
	global_load_lds_dwordx4 v[154:155], off
	v_lshl_add_u64 v[156:157], s[68:69], 0, v[96:97]
	s_mov_b32 m0, s67
	v_lshl_add_u64 v[158:159], s[68:69], 0, v[130:131]
	global_load_lds_dwordx4 v[156:157], off
	s_add_i32 m0, s67, 0x2000
	v_lshl_add_u64 v[182:183], s[6:7], 0, v[134:135]
	global_load_lds_dwordx4 v[158:159], off
	s_mov_b32 m0, s52
	v_lshl_add_u64 v[184:185], s[6:7], 0, v[132:133]
	global_load_lds_dwordx4 v[182:183], off
	s_mov_b32 m0, s53
	s_nop 0
	global_load_lds_dwordx4 v[184:185], off
	s_setprio 1
	s_waitcnt vmcnt(8) lgkmcnt(0)
	s_barrier
	v_mfma_f32_16x16x32_bf16 v[60:63], v[140:143], v[198:201], v[60:63]
	v_mfma_f32_16x16x32_bf16 v[56:59], v[162:165], v[198:201], v[56:59]
	v_mfma_f32_16x16x32_bf16 v[44:47], v[140:143], v[206:209], v[44:47]
	v_mfma_f32_16x16x32_bf16 v[40:43], v[162:165], v[206:209], v[40:43]
	v_mfma_f32_16x16x32_bf16 v[28:31], v[140:143], v[214:217], v[28:31]
	v_mfma_f32_16x16x32_bf16 v[24:27], v[162:165], v[214:217], v[24:27]
	v_mfma_f32_16x16x32_bf16 v[12:15], v[140:143], v[222:225], v[12:15]
	v_mfma_f32_16x16x32_bf16 v[8:11], v[162:165], v[222:225], v[8:11]
	v_mfma_f32_16x16x32_bf16 v[60:63], v[144:147], v[202:205], v[60:63]
	v_mfma_f32_16x16x32_bf16 v[56:59], v[166:169], v[202:205], v[56:59]
	v_mfma_f32_16x16x32_bf16 v[44:47], v[144:147], v[210:213], v[44:47]
	v_mfma_f32_16x16x32_bf16 v[40:43], v[166:169], v[210:213], v[40:43]
	v_mfma_f32_16x16x32_bf16 v[28:31], v[144:147], v[218:221], v[28:31]
	v_mfma_f32_16x16x32_bf16 v[24:27], v[166:169], v[218:221], v[24:27]
	v_mfma_f32_16x16x32_bf16 v[12:15], v[144:147], v[226:229], v[12:15]
	v_mfma_f32_16x16x32_bf16 v[8:11], v[166:169], v[226:229], v[8:11]
	s_setprio 0
	s_setprio 1
	v_mfma_f32_16x16x32_bf16 v[52:55], v[170:173], v[198:201], v[52:55]
	v_mfma_f32_16x16x32_bf16 v[48:51], v[190:193], v[198:201], v[48:51]
	v_mfma_f32_16x16x32_bf16 v[36:39], v[170:173], v[206:209], v[36:39]
	v_mfma_f32_16x16x32_bf16 v[32:35], v[190:193], v[206:209], v[32:35]
	v_mfma_f32_16x16x32_bf16 v[20:23], v[170:173], v[214:217], v[20:23]
	v_mfma_f32_16x16x32_bf16 v[16:19], v[190:193], v[214:217], v[16:19]
	v_mfma_f32_16x16x32_bf16 v[4:7], v[170:173], v[222:225], v[4:7]
	v_mfma_f32_16x16x32_bf16 v[0:3], v[190:193], v[222:225], v[0:3]
	v_mfma_f32_16x16x32_bf16 v[52:55], v[186:189], v[202:205], v[52:55]
	v_mfma_f32_16x16x32_bf16 v[48:51], v[194:197], v[202:205], v[48:51]
	v_mfma_f32_16x16x32_bf16 v[36:39], v[186:189], v[210:213], v[36:39]
	v_mfma_f32_16x16x32_bf16 v[32:35], v[194:197], v[210:213], v[32:35]
	v_mfma_f32_16x16x32_bf16 v[20:23], v[186:189], v[218:221], v[20:23]
	v_mfma_f32_16x16x32_bf16 v[16:19], v[194:197], v[218:221], v[16:19]
	v_mfma_f32_16x16x32_bf16 v[4:7], v[186:189], v[226:229], v[4:7]
	v_mfma_f32_16x16x32_bf16 v[0:3], v[194:197], v[226:229], v[0:3]
	s_setprio 0
	s_barrier
	s_setprio 2
	s_add_i32 s67, 0, 0x18000
	s_add_i32 s68, 0, 0x1c000
	v_add_u32_e32 v166, s67, v151
	v_add_u32_e32 v194, s68, v151
	ds_read_b128 v[140:143], v166
	ds_read_b128 v[144:147], v166 offset:1024
	ds_read_b128 v[162:165], v166 offset:2048
	ds_read_b128 v[166:169], v166 offset:3072
	ds_read_b128 v[170:173], v194
	ds_read_b128 v[186:189], v194 offset:1024
	ds_read_b128 v[190:193], v194 offset:2048
	ds_read_b128 v[194:197], v194 offset:3072
	s_add_u32 s6, s6, s46
	s_addc_u32 s7, s7, 0
	s_mov_b32 m0, s54
	v_lshl_add_u64 v[230:231], s[6:7], 0, v[134:135]
	ds_read_b128 v[198:201], v153 offset:32768
	ds_read_b128 v[202:205], v153 offset:33792
	ds_read_b128 v[206:209], v153 offset:34816
	ds_read_b128 v[210:213], v153 offset:35840
	ds_read_b128 v[214:217], v153 offset:36864
	ds_read_b128 v[218:221], v153 offset:37888
	ds_read_b128 v[222:225], v153 offset:38912
	ds_read_b128 v[226:229], v153 offset:39936
	global_load_lds_dwordx4 v[230:231], off
	v_lshl_add_u64 v[230:231], s[6:7], 0, v[132:133]
	s_mov_b32 m0, s55
	s_nop 0
	global_load_lds_dwordx4 v[230:231], off
	s_setprio 1
	s_waitcnt vmcnt(8) lgkmcnt(0)
	s_barrier
	v_mfma_f32_16x16x32_bf16 v[126:129], v[140:143], v[198:201], v[126:129]
	v_mfma_f32_16x16x32_bf16 v[122:125], v[162:165], v[198:201], v[122:125]
	v_mfma_f32_16x16x32_bf16 v[110:113], v[140:143], v[206:209], v[110:113]
	v_mfma_f32_16x16x32_bf16 v[106:109], v[162:165], v[206:209], v[106:109]
	v_mfma_f32_16x16x32_bf16 v[92:95], v[140:143], v[214:217], v[92:95]
	v_mfma_f32_16x16x32_bf16 v[88:91], v[162:165], v[214:217], v[88:91]
	v_mfma_f32_16x16x32_bf16 v[76:79], v[140:143], v[222:225], v[76:79]
	v_mfma_f32_16x16x32_bf16 v[72:75], v[162:165], v[222:225], v[72:75]
	v_mfma_f32_16x16x32_bf16 v[126:129], v[144:147], v[202:205], v[126:129]
	v_mfma_f32_16x16x32_bf16 v[122:125], v[166:169], v[202:205], v[122:125]
	v_mfma_f32_16x16x32_bf16 v[110:113], v[144:147], v[210:213], v[110:113]
	v_mfma_f32_16x16x32_bf16 v[106:109], v[166:169], v[210:213], v[106:109]
	v_mfma_f32_16x16x32_bf16 v[92:95], v[144:147], v[218:221], v[92:95]
	v_mfma_f32_16x16x32_bf16 v[88:91], v[166:169], v[218:221], v[88:91]
	v_mfma_f32_16x16x32_bf16 v[76:79], v[144:147], v[226:229], v[76:79]
	v_mfma_f32_16x16x32_bf16 v[72:75], v[166:169], v[226:229], v[72:75]
	s_setprio 0
	s_setprio 1
	v_mfma_f32_16x16x32_bf16 v[118:121], v[170:173], v[198:201], v[118:121]
	v_mfma_f32_16x16x32_bf16 v[114:117], v[190:193], v[198:201], v[114:117]
	v_mfma_f32_16x16x32_bf16 v[102:105], v[170:173], v[206:209], v[102:105]
	v_mfma_f32_16x16x32_bf16 v[98:101], v[190:193], v[206:209], v[98:101]
	v_mfma_f32_16x16x32_bf16 v[84:87], v[170:173], v[214:217], v[84:87]
	v_mfma_f32_16x16x32_bf16 v[80:83], v[190:193], v[214:217], v[80:83]
	v_mfma_f32_16x16x32_bf16 v[68:71], v[170:173], v[222:225], v[68:71]
	v_mfma_f32_16x16x32_bf16 v[64:67], v[190:193], v[222:225], v[64:67]
	v_mfma_f32_16x16x32_bf16 v[118:121], v[186:189], v[202:205], v[118:121]
	v_mfma_f32_16x16x32_bf16 v[114:117], v[194:197], v[202:205], v[114:117]
	v_mfma_f32_16x16x32_bf16 v[102:105], v[186:189], v[210:213], v[102:105]
	v_mfma_f32_16x16x32_bf16 v[98:101], v[194:197], v[210:213], v[98:101]
	v_mfma_f32_16x16x32_bf16 v[84:87], v[186:189], v[218:221], v[84:87]
	v_mfma_f32_16x16x32_bf16 v[80:83], v[194:197], v[218:221], v[80:83]
	v_mfma_f32_16x16x32_bf16 v[68:71], v[186:189], v[226:229], v[68:71]
	v_mfma_f32_16x16x32_bf16 v[64:67], v[194:197], v[226:229], v[64:67]
	s_setprio 0
	s_barrier
	s_setprio 2
	s_add_i32 s6, s67, s51
	v_lshl_add_u64 v[148:149], v[148:149], 0, s[16:17]
	s_mov_b32 m0, s6
	ds_read_b128 v[198:201], v153 offset:49152
	ds_read_b128 v[202:205], v153 offset:50176
	ds_read_b128 v[206:209], v153 offset:51200
	ds_read_b128 v[210:213], v153 offset:52224
	ds_read_b128 v[214:217], v153 offset:53248
	ds_read_b128 v[218:221], v153 offset:54272
	ds_read_b128 v[222:225], v153 offset:55296
	ds_read_b128 v[226:229], v153 offset:56320
	global_load_lds_dwordx4 v[148:149], off
	v_lshl_add_u64 v[148:149], v[154:155], 0, s[16:17]
	s_add_i32 m0, s6, 0x2000
	s_add_i32 s6, s68, s51
	global_load_lds_dwordx4 v[148:149], off
	v_lshl_add_u64 v[148:149], v[156:157], 0, s[16:17]
	s_mov_b32 m0, s6
	s_nop 0
	global_load_lds_dwordx4 v[148:149], off
	v_lshl_add_u64 v[148:149], v[158:159], 0, s[16:17]
	s_add_i32 m0, s6, 0x2000
	s_nop 0
	global_load_lds_dwordx4 v[148:149], off
	v_lshl_add_u64 v[148:149], v[182:183], 0, s[16:17]
	s_mov_b32 m0, s56
	s_nop 0
	global_load_lds_dwordx4 v[148:149], off
	v_lshl_add_u64 v[148:149], v[184:185], 0, s[16:17]
	s_mov_b32 m0, s57
	s_nop 0
	global_load_lds_dwordx4 v[148:149], off
	s_setprio 1
	s_waitcnt vmcnt(8) lgkmcnt(0)
	s_barrier
	v_mfma_f32_16x16x32_bf16 v[60:63], v[140:143], v[198:201], v[60:63]
	v_mfma_f32_16x16x32_bf16 v[56:59], v[162:165], v[198:201], v[56:59]
	v_mfma_f32_16x16x32_bf16 v[44:47], v[140:143], v[206:209], v[44:47]
	v_mfma_f32_16x16x32_bf16 v[40:43], v[162:165], v[206:209], v[40:43]
	v_mfma_f32_16x16x32_bf16 v[28:31], v[140:143], v[214:217], v[28:31]
	v_mfma_f32_16x16x32_bf16 v[24:27], v[162:165], v[214:217], v[24:27]
	v_mfma_f32_16x16x32_bf16 v[12:15], v[140:143], v[222:225], v[12:15]
	v_mfma_f32_16x16x32_bf16 v[8:11], v[162:165], v[222:225], v[8:11]
	v_mfma_f32_16x16x32_bf16 v[60:63], v[144:147], v[202:205], v[60:63]
	v_mfma_f32_16x16x32_bf16 v[56:59], v[166:169], v[202:205], v[56:59]
	v_mfma_f32_16x16x32_bf16 v[44:47], v[144:147], v[210:213], v[44:47]
	v_mfma_f32_16x16x32_bf16 v[40:43], v[166:169], v[210:213], v[40:43]
	v_mfma_f32_16x16x32_bf16 v[28:31], v[144:147], v[218:221], v[28:31]
	v_mfma_f32_16x16x32_bf16 v[24:27], v[166:169], v[218:221], v[24:27]
	v_mfma_f32_16x16x32_bf16 v[12:15], v[144:147], v[226:229], v[12:15]
	v_mfma_f32_16x16x32_bf16 v[8:11], v[166:169], v[226:229], v[8:11]
	s_setprio 0
	s_setprio 1
	v_mfma_f32_16x16x32_bf16 v[52:55], v[170:173], v[198:201], v[52:55]
	v_mfma_f32_16x16x32_bf16 v[48:51], v[190:193], v[198:201], v[48:51]
	v_mfma_f32_16x16x32_bf16 v[36:39], v[170:173], v[206:209], v[36:39]
	v_mfma_f32_16x16x32_bf16 v[32:35], v[190:193], v[206:209], v[32:35]
	v_mfma_f32_16x16x32_bf16 v[20:23], v[170:173], v[214:217], v[20:23]
	v_mfma_f32_16x16x32_bf16 v[16:19], v[190:193], v[214:217], v[16:19]
	v_mfma_f32_16x16x32_bf16 v[4:7], v[170:173], v[222:225], v[4:7]
	v_mfma_f32_16x16x32_bf16 v[0:3], v[190:193], v[222:225], v[0:3]
	v_mfma_f32_16x16x32_bf16 v[52:55], v[186:189], v[202:205], v[52:55]
	v_mfma_f32_16x16x32_bf16 v[48:51], v[194:197], v[202:205], v[48:51]
	v_mfma_f32_16x16x32_bf16 v[36:39], v[186:189], v[210:213], v[36:39]
	v_mfma_f32_16x16x32_bf16 v[32:35], v[194:197], v[210:213], v[32:35]
	v_mfma_f32_16x16x32_bf16 v[20:23], v[186:189], v[218:221], v[20:23]
	v_mfma_f32_16x16x32_bf16 v[16:19], v[194:197], v[218:221], v[16:19]
	v_mfma_f32_16x16x32_bf16 v[4:7], v[186:189], v[226:229], v[4:7]
	v_mfma_f32_16x16x32_bf16 v[0:3], v[194:197], v[226:229], v[0:3]
	s_setprio 0
	s_barrier
	s_setprio 2
	s_add_u32 s4, s4, 0x100
	s_addc_u32 s5, s5, 0
	s_add_u32 s14, s14, 0x100
	s_addc_u32 s15, s15, 0
	s_cmp_ge_u32 s66, s59
	s_mov_b32 s6, s66
	s_cbranch_scc0 .LBB0_490
	s_and_b64 vcc, exec, s[36:37]
	s_cbranch_vccz .LBB0_493
	s_barrier
